# v015 plus: out-proj and MLP-down (residual epilogues) stage weight rows so a wave's halves are adjacent, load the second half's base at offset 64, and store 8 rows x 128 bytes per instruction
# baseline (speedup 1.0000x reference)
.LBB0_468:
	s_or_b64 exec, exec, s[4:5]
	v_readlane_b32 s4, v254, 38
	v_readlane_b32 s5, v254, 39
	s_lshl_b64 s[6:7], s[4:5], 2
	v_readlane_b32 s4, v254, 40
	v_readlane_b32 s5, v254, 41
	s_add_u32 s0, s4, s6
	v_readlane_b32 s18, v255, 52
	s_addc_u32 s5, s5, s7
	v_readlane_b32 s19, v255, 53
	s_add_u32 s4, s0, 0x40000
	s_mov_b64 s[14:15], s[82:83]
	s_mov_b64 s[12:13], s[82:83]
	s_mov_b64 s[42:43], s[82:83]
	s_mov_b64 s[40:41], s[82:83]
	v_mov_b32_e32 v16, v224
	v_cndmask_b32_e64 v0, 0, 1, s[18:19]
	s_addc_u32 s5, s5, 0
	s_waitcnt lgkmcnt(0)
	s_barrier
	v_cmp_ne_u32_e64 s[38:39], 1, v0
	s_andn2_b64 vcc, exec, s[18:19]
	v_readfirstlane_b32 s20, v16
	s_cbranch_vccnz .LBB0_504
	v_lshlrev_b32_e32 v0, 4, v16
	v_add_u32_e32 v2, 0x2000, v0
	v_ashrrev_i32_e32 v3, 31, v2
	v_lshrrev_b32_e32 v3, 22, v3
	v_add_u32_e32 v3, v2, v3
	v_ashrrev_i32_e32 v10, 10, v3
	v_mul_i32_i24_e32 v3, 0x400, v10
	v_sub_u32_e32 v2, v2, v3
	v_lshrrev_b32_e32 v3, 4, v2
	s_add_u32 s0, s14, 0x30000000
	v_bitop3_b32 v2, v3, v2, 32 bitop3:0x6c
	s_addc_u32 s17, s15, 0
	v_readlane_b32 s14, v254, 26
	v_ashrrev_i32_e32 v3, 31, v2
	v_readlane_b32 s15, v254, 27
	v_lshrrev_b32_e32 v3, 26, v3
	s_and_b64 s[14:15], s[14:15], exec
	v_add_u32_e32 v3, v2, v3
	v_lshlrev_b32_e32 v4, 3, v10
	s_mov_b32 s14, 0xa00000
	v_ashrrev_i32_e32 v11, 6, v3
	v_and_b32_e32 v4, -16, v4
	s_cselect_b32 s14, s14, 0x1200000
	v_add_u32_e32 v4, v11, v4
	s_add_u32 s60, s12, s14
	v_and_b32_e32 v5, 3, v11
	s_mov_b32 s12, 0x1fffe0
	v_lshrrev_b32_e32 v6, 2, v4
	v_lshlrev_b32_e32 v7, 1, v4
	v_and_or_b32 v5, v4, s12, v5
	v_and_b32_e32 v6, 4, v6
	v_and_b32_e32 v7, 24, v7
	v_and_b32_e32 v3, 0xc0, v3
	v_or3_b32 v5, v5, v6, v7
	v_sub_u32_e32 v2, v2, v3
	v_mov_b32_e32 v7, 1
	v_lshlrev_b32_e32 v6, 5, v10
	v_ashrrev_i16_sdwa v2, v7, sext(v2) dst_sel:DWORD dst_unused:UNUSED_PAD src0_sel:DWORD src1_sel:BYTE_0
	v_and_b32_e32 v6, 32, v6
	v_bfe_i32 v12, v2, 0, 16
	v_add_lshl_u32 v2, v6, v12, 1
	s_waitcnt vmcnt(0)
	v_lshl_add_u32 v154, v5, 11, v2
	v_lshl_add_u32 v156, v4, 11, v2
	v_bfe_i32 v2, v16, 27, 1
	v_lshrrev_b32_e32 v2, 22, v2
	v_add_u32_e32 v2, v0, v2
	v_and_b32_e32 v2, 0xfffffc00, v2
	v_sub_u32_e32 v0, v0, v2
	v_lshrrev_b32_e32 v2, 4, v0
	v_ashrrev_i32_e32 v3, 31, v16
	v_bitop3_b32 v0, v2, v0, 32 bitop3:0x6c
	v_lshrrev_b32_e32 v3, 26, v3
	v_ashrrev_i32_e32 v2, 31, v0
	v_add_u32_e32 v3, v16, v3
	v_lshrrev_b32_e32 v2, 26, v2
	v_ashrrev_i32_e32 v14, 6, v3
	v_add_u32_e32 v2, v0, v2
	v_lshlrev_b32_e32 v3, 3, v14
	v_ashrrev_i32_e32 v13, 6, v2
	v_and_b32_e32 v3, -16, v3
	v_add_u32_e32 v3, v13, v3
	v_and_b32_e32 v4, 3, v13
	v_lshrrev_b32_e32 v5, 2, v3
	v_lshlrev_b32_e32 v6, 1, v3
	v_and_b32_e32 v2, 0xc0, v2
	s_addc_u32 s61, s13, 0
	s_ashr_i32 s21, s20, 6
	v_and_or_b32 v4, v3, s12, v4
	v_and_b32_e32 v5, 4, v5
	v_and_b32_e32 v6, 24, v6
	v_sub_u32_e32 v0, v0, v2
	s_ashr_i32 s28, s20, 8
	s_lshl_b32 s62, s21, 10
	v_or3_b32 v4, v4, v5, v6
	v_lshlrev_b32_e32 v5, 5, v14
	v_ashrrev_i16_sdwa v0, v7, sext(v0) dst_sel:DWORD dst_unused:UNUSED_PAD src0_sel:DWORD src1_sel:BYTE_0
	v_readlane_b32 s12, v254, 9
	v_and_b32_e32 v5, 32, v5
	v_bfe_i32 v15, v0, 0, 16
	v_readlane_b32 s13, v254, 10
	s_add_u32 s12, s60, s12
	v_add_lshl_u32 v2, v5, v15, 1
	s_addc_u32 s13, s61, s13
	s_add_i32 s63, s62, 0
	v_lshl_add_u32 v0, v4, 11, v2
	v_lshrrev_b32_e32 v248, 8, v224
	v_lshl_add_u32 v0, v248, 16, v0
	v_lshl_add_u32 v154, v248, 16, v154
	v_add_u32_e32 v154, 0x20000, v154
	s_add_i32 m0, s63, 0x10000
	v_lshl_add_u32 v158, v3, 11, v2
	global_load_lds_dwordx4 v0, s[12:13]
	s_add_i32 m0, s63, 0x12000
	s_add_u32 s14, s12, 0x10000
	global_load_lds_dwordx4 v154, s[12:13]
	s_addc_u32 s15, s13, 0
	s_add_i32 m0, s63, 0x14000
	v_mov_b32_e32 v155, v1
	global_load_lds_dwordx4 v0, s[14:15]
	s_add_i32 m0, s63, 0x16000
	v_mov_b32_e32 v159, v1
	global_load_lds_dwordx4 v154, s[14:15]
	v_readlane_b32 s14, v254, 7
	v_readlane_b32 s15, v254, 8
	s_add_u32 s14, s0, s14
	s_addc_u32 s15, s17, s15
	s_add_i32 s64, s63, 0x2000
	s_mov_b32 m0, s63
	s_add_u32 s18, s14, 0x40000
	global_load_lds_dwordx4 v158, s[14:15]
	s_mov_b32 m0, s64
	s_addc_u32 s19, s15, 0
	s_add_i32 s65, s63, 0x4000
	global_load_lds_dwordx4 v156, s[14:15]
	s_mov_b32 m0, s65
	s_add_i32 s66, s63, 0x6000
	global_load_lds_dwordx4 v158, s[18:19]
	s_mov_b32 m0, s66
	v_mov_b32_e32 v157, v1
	global_load_lds_dwordx4 v156, s[18:19]
	s_cmp_eq_u32 s28, 1
	v_lshl_add_u64 v[8:9], s[12:13], 0, v[0:1]
	v_lshl_add_u64 v[6:7], s[12:13], 0, v[154:155]
	v_lshl_add_u64 v[2:3], s[14:15], 0, v[158:159]
	s_cselect_b64 s[18:19], -1, 0
	s_cmp_lg_u32 s28, 1
	v_lshl_add_u64 v[4:5], s[14:15], 0, v[156:157]
	s_cbranch_scc1 .LBB0_471
	s_barrier
.LBB0_471:
	s_add_u32 s44, s42, 0xc000000
	s_addc_u32 s45, s43, 0
	s_add_u32 s46, s40, 0x4000000
	v_bfe_u32 v17, v16, 4, 2
	s_addc_u32 s47, s41, 0
	v_and_b32_e32 v18, 15, v16
	v_lshlrev_b32_e32 v19, 4, v17
	v_lshlrev_b32_e32 v16, 2, v16
	s_lshl_b32 s21, s21, 5
	v_lshl_or_b32 v182, s28, 6, v18
	v_lshl_or_b32 v18, v18, 6, v19
	s_lshl_b32 s28, s28, 13
	v_and_b32_e32 v16, 32, v16
	s_and_b32 s21, s21, 0x60
	s_add_i32 m0, s63, 0x18000
	v_lshl_add_u64 v[8:9], v[8:9], 0, s[10:11]
	v_bitop3_b32 v19, v18, s28, v16 bitop3:0xde
	s_lshl_b32 s28, s21, 7
	s_waitcnt vmcnt(2)
	s_barrier
	global_load_lds_dwordx4 v[8:9], off
	v_lshl_add_u64 v[6:7], v[6:7], 0, s[10:11]
	s_add_i32 m0, s63, 0x1a000
	s_add_i32 s67, s63, 0x8000
	s_add_i32 s68, s63, 0xa000
	v_bitop3_b32 v183, v18, s28, v16 bitop3:0xde
	global_load_lds_dwordx4 v[6:7], off
	v_lshl_add_u64 v[2:3], v[2:3], 0, s[10:11]
	s_mov_b32 m0, s67
	s_add_u32 s28, s12, 0x10080
	global_load_lds_dwordx4 v[2:3], off
	v_lshl_add_u64 v[2:3], v[4:5], 0, s[10:11]
	s_mov_b32 m0, s68
	s_addc_u32 s29, s13, 0
	global_load_lds_dwordx4 v[2:3], off
	s_add_i32 m0, s63, 0x1c000
	v_lshl_add_u64 v[2:3], s[28:29], 0, v[0:1]
	global_load_lds_dwordx4 v[2:3], off
	v_lshl_add_u64 v[2:3], s[28:29], 0, v[154:155]
	s_add_i32 m0, s63, 0x1e000
	s_cmpk_lt_u32 s20, 0x100
	global_load_lds_dwordx4 v[2:3], off
	v_lshlrev_b32_e32 v2, 14, v10
	v_and_b32_e32 v2, 0xffff8000, v2
	v_lshl_add_u32 v2, v11, 11, v2
	v_and_b32_e32 v3, 1, v10
	v_lshl_or_b32 v2, v3, 6, v2
	v_lshl_add_u32 v160, v12, 1, v2
	v_lshlrev_b32_e32 v2, 14, v14
	v_and_b32_e32 v2, 0xffff8000, v2
	s_waitcnt vmcnt(6)
	v_lshl_add_u32 v2, v13, 11, v2
	v_and_b32_e32 v3, 1, v14
	v_lshl_or_b32 v2, v3, 6, v2
	v_readlane_b32 s26, v254, 11
	s_cselect_b64 s[48:49], -1, 0
	s_mov_b32 s69, 0
	v_cmp_eq_u32_e64 s[40:41], 0, v17
	v_lshl_or_b32 v184, v17, 3, s21
	v_add_u32_e32 v184, s21, v184
	v_mov_b32_e32 v161, v1
	v_lshl_add_u32 v162, v15, 1, v2
	v_mov_b32_e32 v163, v1
	v_add_u32_e32 v185, 0, v19
	v_readlane_b32 s20, v255, 59
	s_mov_b32 s21, s26
	s_barrier
	v_readlane_b32 s27, v254, 12
	v_and_b32_e32 v249, 8, v228
	v_mul_u32_u24_e32 v250, 0x7f8, v249
	v_sub_u32_e32 v250, 0, v250
	v_ashrrev_i32_e32 v251, 31, v250
	s_mov_b32 s98, 0x00ff00ff
	s_mov_b32 s99, 0x00ff00ff
	s_mov_b32 s100, 0x4000
	s_mov_b32 s101, 0
	s_branch .LBB0_474

.LBB0_481:
	s_add_i32 s70, 0, 0x10000
	s_add_i32 s72, 0, 0x14000
	v_add_u32_e32 v134, s70, v183
	v_add_u32_e32 v168, s72, v183
	ds_read_b128 v[114:117], v134
	ds_read_b128 v[118:121], v134 offset:1024
	ds_read_b128 v[122:125], v134 offset:2048
	ds_read_b128 v[134:137], v134 offset:3072
	ds_read_b128 v[146:149], v168
	ds_read_b128 v[150:153], v168 offset:1024
	ds_read_b128 v[164:167], v168 offset:2048
	ds_read_b128 v[168:171], v168 offset:3072
	v_lshl_add_u64 v[180:181], s[12:13], 0, v[162:163]
	s_add_i32 m0, s63, 0xc000
	ds_read_b128 v[172:175], v185
	ds_read_b128 v[176:179], v185 offset:1024
	ds_read_b128 v[186:189], v185 offset:2048
	ds_read_b128 v[190:193], v185 offset:3072
	ds_read_b128 v[202:205], v185 offset:4096
	ds_read_b128 v[206:209], v185 offset:5120
	ds_read_b128 v[210:213], v185 offset:6144
	ds_read_b128 v[214:217], v185 offset:7168
	s_add_u32 s14, s12, 0xfffc0080
	s_addc_u32 s15, s13, -1
	s_cmp_eq_u32 s53, 12
	s_cselect_b32 s59, s28, s15
	s_cselect_b32 s58, s29, s14
	s_cselect_b32 s15, s33, s51
	s_cselect_b32 s14, s36, s37
	global_load_lds_dwordx4 v[180:181], off
	v_lshl_add_u64 v[180:181], s[12:13], 0, v[160:161]
	s_add_i32 m0, s63, 0xe000
	s_nop 0
	global_load_lds_dwordx4 v[180:181], off
	s_waitcnt vmcnt(8)
	s_waitcnt lgkmcnt(0)
	s_setprio 1
	s_barrier
	v_mfma_f32_16x16x32_bf16 v[142:145], v[114:117], v[172:175], v[142:145]
	v_mfma_f32_16x16x32_bf16 v[138:141], v[122:125], v[172:175], v[138:141]
	v_mfma_f32_16x16x32_bf16 v[110:113], v[114:117], v[186:189], v[110:113]
	v_mfma_f32_16x16x32_bf16 v[106:109], v[122:125], v[186:189], v[106:109]
	v_mfma_f32_16x16x32_bf16 v[94:97], v[114:117], v[202:205], v[94:97]
	v_mfma_f32_16x16x32_bf16 v[90:93], v[122:125], v[202:205], v[90:93]
	v_mfma_f32_16x16x32_bf16 v[78:81], v[114:117], v[210:213], v[78:81]
	v_mfma_f32_16x16x32_bf16 v[74:77], v[122:125], v[210:213], v[74:77]
	v_mfma_f32_16x16x32_bf16 v[142:145], v[118:121], v[176:179], v[142:145]
	v_mfma_f32_16x16x32_bf16 v[138:141], v[134:137], v[176:179], v[138:141]
	v_mfma_f32_16x16x32_bf16 v[110:113], v[118:121], v[190:193], v[110:113]
	v_mfma_f32_16x16x32_bf16 v[106:109], v[134:137], v[190:193], v[106:109]
	v_mfma_f32_16x16x32_bf16 v[94:97], v[118:121], v[206:209], v[94:97]
	v_mfma_f32_16x16x32_bf16 v[90:93], v[134:137], v[206:209], v[90:93]
	v_mfma_f32_16x16x32_bf16 v[78:81], v[118:121], v[214:217], v[78:81]
	v_mfma_f32_16x16x32_bf16 v[74:77], v[134:137], v[214:217], v[74:77]
	v_mfma_f32_16x16x32_bf16 v[130:133], v[146:149], v[172:175], v[130:133]
	v_mfma_f32_16x16x32_bf16 v[126:129], v[164:167], v[172:175], v[126:129]
	v_mfma_f32_16x16x32_bf16 v[102:105], v[146:149], v[186:189], v[102:105]
	v_mfma_f32_16x16x32_bf16 v[98:101], v[164:167], v[186:189], v[98:101]
	v_mfma_f32_16x16x32_bf16 v[86:89], v[146:149], v[202:205], v[86:89]
	v_mfma_f32_16x16x32_bf16 v[82:85], v[164:167], v[202:205], v[82:85]
	v_mfma_f32_16x16x32_bf16 v[70:73], v[146:149], v[210:213], v[70:73]
	v_mfma_f32_16x16x32_bf16 v[66:69], v[164:167], v[210:213], v[66:69]
	v_mfma_f32_16x16x32_bf16 v[130:133], v[150:153], v[176:179], v[130:133]
	v_mfma_f32_16x16x32_bf16 v[126:129], v[168:171], v[176:179], v[126:129]
	v_mfma_f32_16x16x32_bf16 v[102:105], v[150:153], v[190:193], v[102:105]
	v_mfma_f32_16x16x32_bf16 v[98:101], v[168:171], v[190:193], v[98:101]
	v_mfma_f32_16x16x32_bf16 v[86:89], v[150:153], v[206:209], v[86:89]
	v_mfma_f32_16x16x32_bf16 v[82:85], v[168:171], v[206:209], v[82:85]
	v_mfma_f32_16x16x32_bf16 v[70:73], v[150:153], v[214:217], v[70:73]
	v_mfma_f32_16x16x32_bf16 v[66:69], v[168:171], v[214:217], v[66:69]
	s_barrier
	s_setprio 0
	s_add_i32 s70, s70, s62
	v_lshl_add_u64 v[180:181], s[14:15], 0, v[0:1]
	s_mov_b32 m0, s70
	ds_read_b128 v[172:175], v185 offset:16384
	ds_read_b128 v[176:179], v185 offset:17408
	ds_read_b128 v[186:189], v185 offset:18432
	ds_read_b128 v[190:193], v185 offset:19456
	ds_read_b128 v[202:205], v185 offset:20480
	ds_read_b128 v[206:209], v185 offset:21504
	ds_read_b128 v[210:213], v185 offset:22528
	ds_read_b128 v[214:217], v185 offset:23552
	global_load_lds_dwordx4 v[180:181], off
	s_add_i32 m0, s70, 0x2000
	s_add_u32 s70, s14, 0x10000
	v_lshl_add_u64 v[218:219], s[14:15], 0, v[154:155]
	s_addc_u32 s71, s15, 0
	s_add_i32 s72, s72, s62
	global_load_lds_dwordx4 v[218:219], off
	v_lshl_add_u64 v[220:221], s[70:71], 0, v[0:1]
	s_mov_b32 m0, s72
	v_lshl_add_u64 v[222:223], s[58:59], 0, v[156:157]
	global_load_lds_dwordx4 v[220:221], off
	v_lshl_add_u64 v[220:221], s[70:71], 0, v[154:155]
	s_add_i32 m0, s72, 0x2000
	s_nop 0
	global_load_lds_dwordx4 v[220:221], off
	v_lshl_add_u64 v[220:221], s[58:59], 0, v[158:159]
	s_mov_b32 m0, s63
	s_nop 0
	global_load_lds_dwordx4 v[220:221], off
	s_mov_b32 m0, s64
	s_nop 0
	global_load_lds_dwordx4 v[222:223], off
	s_waitcnt vmcnt(8)
	s_waitcnt lgkmcnt(0)
	s_setprio 1
	s_barrier
	v_mfma_f32_16x16x32_bf16 v[62:65], v[114:117], v[172:175], v[62:65]
	v_mfma_f32_16x16x32_bf16 v[58:61], v[122:125], v[172:175], v[58:61]
	v_mfma_f32_16x16x32_bf16 v[46:49], v[114:117], v[186:189], v[46:49]
	v_mfma_f32_16x16x32_bf16 v[42:45], v[122:125], v[186:189], v[42:45]
	v_mfma_f32_16x16x32_bf16 v[30:33], v[114:117], v[202:205], v[30:33]
	v_mfma_f32_16x16x32_bf16 v[26:29], v[122:125], v[202:205], v[26:29]
	v_mfma_f32_16x16x32_bf16 v[14:17], v[114:117], v[210:213], v[14:17]
	v_mfma_f32_16x16x32_bf16 v[10:13], v[122:125], v[210:213], v[10:13]
	v_mfma_f32_16x16x32_bf16 v[62:65], v[118:121], v[176:179], v[62:65]
	v_mfma_f32_16x16x32_bf16 v[58:61], v[134:137], v[176:179], v[58:61]
	v_mfma_f32_16x16x32_bf16 v[46:49], v[118:121], v[190:193], v[46:49]
	v_mfma_f32_16x16x32_bf16 v[42:45], v[134:137], v[190:193], v[42:45]
	v_mfma_f32_16x16x32_bf16 v[30:33], v[118:121], v[206:209], v[30:33]
	v_mfma_f32_16x16x32_bf16 v[26:29], v[134:137], v[206:209], v[26:29]
	v_mfma_f32_16x16x32_bf16 v[14:17], v[118:121], v[214:217], v[14:17]
	v_mfma_f32_16x16x32_bf16 v[10:13], v[134:137], v[214:217], v[10:13]
	v_mfma_f32_16x16x32_bf16 v[54:57], v[146:149], v[172:175], v[54:57]
	v_mfma_f32_16x16x32_bf16 v[50:53], v[164:167], v[172:175], v[50:53]
	v_mfma_f32_16x16x32_bf16 v[38:41], v[146:149], v[186:189], v[38:41]
	v_mfma_f32_16x16x32_bf16 v[34:37], v[164:167], v[186:189], v[34:37]
	v_mfma_f32_16x16x32_bf16 v[22:25], v[146:149], v[202:205], v[22:25]
	v_mfma_f32_16x16x32_bf16 v[18:21], v[164:167], v[202:205], v[18:21]
	v_mfma_f32_16x16x32_bf16 v[6:9], v[146:149], v[210:213], v[6:9]
	v_mfma_f32_16x16x32_bf16 v[2:5], v[164:167], v[210:213], v[2:5]
	v_mfma_f32_16x16x32_bf16 v[54:57], v[150:153], v[176:179], v[54:57]
	v_mfma_f32_16x16x32_bf16 v[50:53], v[168:171], v[176:179], v[50:53]
	v_mfma_f32_16x16x32_bf16 v[38:41], v[150:153], v[190:193], v[38:41]
	v_mfma_f32_16x16x32_bf16 v[34:37], v[168:171], v[190:193], v[34:37]
	v_mfma_f32_16x16x32_bf16 v[22:25], v[150:153], v[206:209], v[22:25]
	v_mfma_f32_16x16x32_bf16 v[18:21], v[168:171], v[206:209], v[18:21]
	v_mfma_f32_16x16x32_bf16 v[6:9], v[150:153], v[214:217], v[6:9]
	v_mfma_f32_16x16x32_bf16 v[2:5], v[168:171], v[214:217], v[2:5]
	s_barrier
	s_setprio 0
	s_add_i32 s70, 0, 0x18000
	s_add_i32 s71, 0, 0x1c000
	v_add_u32_e32 v134, s70, v183
	v_add_u32_e32 v168, s71, v183
	ds_read_b128 v[114:117], v134
	ds_read_b128 v[118:121], v134 offset:1024
	ds_read_b128 v[122:125], v134 offset:2048
	ds_read_b128 v[134:137], v134 offset:3072
	ds_read_b128 v[146:149], v168
	ds_read_b128 v[150:153], v168 offset:1024
	ds_read_b128 v[164:167], v168 offset:2048
	ds_read_b128 v[168:171], v168 offset:3072
	s_add_u32 s58, s58, 0x40000
	s_addc_u32 s59, s59, 0
	s_mov_b32 m0, s65
	v_lshl_add_u64 v[232:233], s[58:59], 0, v[158:159]
	ds_read_b128 v[172:175], v185 offset:32768
	ds_read_b128 v[176:179], v185 offset:33792
	ds_read_b128 v[186:189], v185 offset:34816
	ds_read_b128 v[190:193], v185 offset:35840
	ds_read_b128 v[202:205], v185 offset:36864
	ds_read_b128 v[206:209], v185 offset:37888
	ds_read_b128 v[210:213], v185 offset:38912
	ds_read_b128 v[214:217], v185 offset:39936
	global_load_lds_dwordx4 v[232:233], off
	v_lshl_add_u64 v[232:233], s[58:59], 0, v[156:157]
	s_mov_b32 m0, s66
	s_nop 0
	global_load_lds_dwordx4 v[232:233], off
	s_waitcnt vmcnt(8)
	s_waitcnt lgkmcnt(0)
	s_setprio 1
	s_barrier
	v_mfma_f32_16x16x32_bf16 v[142:145], v[114:117], v[172:175], v[142:145]
	v_mfma_f32_16x16x32_bf16 v[138:141], v[122:125], v[172:175], v[138:141]
	v_mfma_f32_16x16x32_bf16 v[110:113], v[114:117], v[186:189], v[110:113]
	v_mfma_f32_16x16x32_bf16 v[106:109], v[122:125], v[186:189], v[106:109]
	v_mfma_f32_16x16x32_bf16 v[94:97], v[114:117], v[202:205], v[94:97]
	v_mfma_f32_16x16x32_bf16 v[90:93], v[122:125], v[202:205], v[90:93]
	v_mfma_f32_16x16x32_bf16 v[78:81], v[114:117], v[210:213], v[78:81]
	v_mfma_f32_16x16x32_bf16 v[74:77], v[122:125], v[210:213], v[74:77]
	v_mfma_f32_16x16x32_bf16 v[142:145], v[118:121], v[176:179], v[142:145]
	v_mfma_f32_16x16x32_bf16 v[138:141], v[134:137], v[176:179], v[138:141]
	v_mfma_f32_16x16x32_bf16 v[110:113], v[118:121], v[190:193], v[110:113]
	v_mfma_f32_16x16x32_bf16 v[106:109], v[134:137], v[190:193], v[106:109]
	v_mfma_f32_16x16x32_bf16 v[94:97], v[118:121], v[206:209], v[94:97]
	v_mfma_f32_16x16x32_bf16 v[90:93], v[134:137], v[206:209], v[90:93]
	v_mfma_f32_16x16x32_bf16 v[78:81], v[118:121], v[214:217], v[78:81]
	v_mfma_f32_16x16x32_bf16 v[74:77], v[134:137], v[214:217], v[74:77]
	v_mfma_f32_16x16x32_bf16 v[130:133], v[146:149], v[172:175], v[130:133]
	v_mfma_f32_16x16x32_bf16 v[126:129], v[164:167], v[172:175], v[126:129]
	v_mfma_f32_16x16x32_bf16 v[102:105], v[146:149], v[186:189], v[102:105]
	v_mfma_f32_16x16x32_bf16 v[98:101], v[164:167], v[186:189], v[98:101]
	v_mfma_f32_16x16x32_bf16 v[86:89], v[146:149], v[202:205], v[86:89]
	v_mfma_f32_16x16x32_bf16 v[82:85], v[164:167], v[202:205], v[82:85]
	v_mfma_f32_16x16x32_bf16 v[70:73], v[146:149], v[210:213], v[70:73]
	v_mfma_f32_16x16x32_bf16 v[66:69], v[164:167], v[210:213], v[66:69]
	v_mfma_f32_16x16x32_bf16 v[130:133], v[150:153], v[176:179], v[130:133]
	v_mfma_f32_16x16x32_bf16 v[126:129], v[168:171], v[176:179], v[126:129]
	v_mfma_f32_16x16x32_bf16 v[102:105], v[150:153], v[190:193], v[102:105]
	v_mfma_f32_16x16x32_bf16 v[98:101], v[168:171], v[190:193], v[98:101]
	v_mfma_f32_16x16x32_bf16 v[86:89], v[150:153], v[206:209], v[86:89]
	v_mfma_f32_16x16x32_bf16 v[82:85], v[168:171], v[206:209], v[82:85]
	v_mfma_f32_16x16x32_bf16 v[70:73], v[150:153], v[214:217], v[70:73]
	v_mfma_f32_16x16x32_bf16 v[66:69], v[168:171], v[214:217], v[66:69]
	s_barrier
	s_setprio 0
	s_add_i32 s58, s70, s62
	v_lshl_add_u64 v[180:181], v[180:181], 0, s[10:11]
	s_mov_b32 m0, s58
	ds_read_b128 v[172:175], v185 offset:49152
	ds_read_b128 v[176:179], v185 offset:50176
	ds_read_b128 v[186:189], v185 offset:51200
	ds_read_b128 v[190:193], v185 offset:52224
	ds_read_b128 v[202:205], v185 offset:53248
	ds_read_b128 v[206:209], v185 offset:54272
	ds_read_b128 v[210:213], v185 offset:55296
	ds_read_b128 v[214:217], v185 offset:56320
	s_add_i32 s53, s53, 2
	s_add_u32 s37, s37, 0x100
	s_addc_u32 s51, s51, 0
	s_add_u32 s12, s12, 0x100
	s_addc_u32 s13, s13, 0
	global_load_lds_dwordx4 v[180:181], off
	s_add_i32 m0, s58, 0x2000
	s_add_u32 s14, s14, 0x10080
	v_lshl_add_u64 v[180:181], v[218:219], 0, s[10:11]
	s_addc_u32 s15, s15, 0
	s_add_i32 s58, s71, s62
	global_load_lds_dwordx4 v[180:181], off
	v_lshl_add_u64 v[180:181], s[14:15], 0, v[0:1]
	s_mov_b32 m0, s58
	s_nop 0
	global_load_lds_dwordx4 v[180:181], off
	v_lshl_add_u64 v[180:181], s[14:15], 0, v[154:155]
	s_add_i32 m0, s58, 0x2000
	s_nop 0
	global_load_lds_dwordx4 v[180:181], off
	v_lshl_add_u64 v[180:181], v[220:221], 0, s[10:11]
	s_mov_b32 m0, s67
	s_nop 0
	global_load_lds_dwordx4 v[180:181], off
	v_lshl_add_u64 v[180:181], v[222:223], 0, s[10:11]
	s_mov_b32 m0, s68
	s_nop 0
	global_load_lds_dwordx4 v[180:181], off
	s_waitcnt vmcnt(8)
	s_waitcnt lgkmcnt(0)
	s_setprio 1
	s_barrier
	v_mfma_f32_16x16x32_bf16 v[62:65], v[114:117], v[172:175], v[62:65]
	v_mfma_f32_16x16x32_bf16 v[58:61], v[122:125], v[172:175], v[58:61]
	v_mfma_f32_16x16x32_bf16 v[46:49], v[114:117], v[186:189], v[46:49]
	v_mfma_f32_16x16x32_bf16 v[42:45], v[122:125], v[186:189], v[42:45]
	v_mfma_f32_16x16x32_bf16 v[30:33], v[114:117], v[202:205], v[30:33]
	v_mfma_f32_16x16x32_bf16 v[26:29], v[122:125], v[202:205], v[26:29]
	v_mfma_f32_16x16x32_bf16 v[14:17], v[114:117], v[210:213], v[14:17]
	v_mfma_f32_16x16x32_bf16 v[10:13], v[122:125], v[210:213], v[10:13]
	v_mfma_f32_16x16x32_bf16 v[62:65], v[118:121], v[176:179], v[62:65]
	v_mfma_f32_16x16x32_bf16 v[58:61], v[134:137], v[176:179], v[58:61]
	v_mfma_f32_16x16x32_bf16 v[46:49], v[118:121], v[190:193], v[46:49]
	v_mfma_f32_16x16x32_bf16 v[42:45], v[134:137], v[190:193], v[42:45]
	v_mfma_f32_16x16x32_bf16 v[30:33], v[118:121], v[206:209], v[30:33]
	v_mfma_f32_16x16x32_bf16 v[26:29], v[134:137], v[206:209], v[26:29]
	v_mfma_f32_16x16x32_bf16 v[14:17], v[118:121], v[214:217], v[14:17]
	v_mfma_f32_16x16x32_bf16 v[10:13], v[134:137], v[214:217], v[10:13]
	v_mfma_f32_16x16x32_bf16 v[54:57], v[146:149], v[172:175], v[54:57]
	v_mfma_f32_16x16x32_bf16 v[50:53], v[164:167], v[172:175], v[50:53]
	v_mfma_f32_16x16x32_bf16 v[38:41], v[146:149], v[186:189], v[38:41]
	v_mfma_f32_16x16x32_bf16 v[34:37], v[164:167], v[186:189], v[34:37]
	v_mfma_f32_16x16x32_bf16 v[22:25], v[146:149], v[202:205], v[22:25]
	v_mfma_f32_16x16x32_bf16 v[18:21], v[164:167], v[202:205], v[18:21]
	v_mfma_f32_16x16x32_bf16 v[6:9], v[146:149], v[210:213], v[6:9]
	v_mfma_f32_16x16x32_bf16 v[2:5], v[164:167], v[210:213], v[2:5]
	v_mfma_f32_16x16x32_bf16 v[54:57], v[150:153], v[176:179], v[54:57]
	v_mfma_f32_16x16x32_bf16 v[50:53], v[168:171], v[176:179], v[50:53]
	v_mfma_f32_16x16x32_bf16 v[38:41], v[150:153], v[190:193], v[38:41]
	v_mfma_f32_16x16x32_bf16 v[34:37], v[168:171], v[190:193], v[34:37]
	v_mfma_f32_16x16x32_bf16 v[22:25], v[150:153], v[206:209], v[22:25]
	v_mfma_f32_16x16x32_bf16 v[18:21], v[168:171], v[206:209], v[18:21]
	v_mfma_f32_16x16x32_bf16 v[6:9], v[150:153], v[214:217], v[6:9]
	v_mfma_f32_16x16x32_bf16 v[2:5], v[168:171], v[214:217], v[2:5]
	s_barrier
	s_setprio 0
	s_cmp_gt_u32 s53, 13
	s_cbranch_scc0 .LBB0_481
	s_and_b64 vcc, exec, s[48:49]
	s_cbranch_vccz .LBB0_484
	s_barrier
.LBB0_484:
	v_lshl_or_b32 v164, s20, 8, v184
	v_lshl_add_u32 v168, s21, 8, v182
	v_ashrrev_i32_e32 v165, 31, v164
	v_lshlrev_b64 v[202:203], 1, v[164:165]
	v_ashrrev_i32_e32 v169, 31, v168
	v_lshl_add_u64 v[166:167], s[44:45], 0, v[202:203]
	v_lshlrev_b64 v[204:205], 11, v[168:169]
	v_lshl_add_u64 v[114:115], v[166:167], 0, v[204:205]
	flat_load_dwordx4 v[186:189], v[114:115]
	flat_load_dwordx4 v[190:193], v[114:115] offset:64
	v_or_b32_e32 v178, 16, v168
	v_ashrrev_i32_e32 v179, 31, v178
	v_or_b32_e32 v174, 32, v168
	v_lshlrev_b64 v[180:181], 11, v[178:179]
	v_ashrrev_i32_e32 v175, 31, v174
	v_or_b32_e32 v170, 48, v168
	v_lshl_add_u64 v[114:115], v[166:167], 0, v[180:181]
	v_lshlrev_b64 v[176:177], 11, v[174:175]
	v_ashrrev_i32_e32 v171, 31, v170
	flat_load_dwordx4 v[150:153], v[114:115]
	flat_load_dwordx4 v[146:149], v[114:115] offset:64
	v_lshl_add_u64 v[114:115], v[166:167], 0, v[176:177]
	v_lshlrev_b64 v[172:173], 11, v[170:171]
	flat_load_dwordx4 v[134:137], v[114:115]
	flat_load_dwordx4 v[122:125], v[114:115] offset:64
	v_lshl_add_u64 v[114:115], v[166:167], 0, v[172:173]
	flat_load_dwordx4 v[118:121], v[114:115]
	s_nop 0
	flat_load_dwordx4 v[114:117], v[114:115] offset:64
	v_lshl_add_u64 v[204:205], s[46:47], 0, v[204:205]
	v_lshl_add_u64 v[202:203], v[204:205], 0, v[202:203]
	s_waitcnt vmcnt(0) lgkmcnt(0)
	v_lshlrev_b32_e32 v206, 16, v186
	v_and_b32_e32 v207, 0xffff0000, v186
	v_lshlrev_b32_e32 v186, 16, v187
	v_and_b32_e32 v187, 0xffff0000, v187
	v_lshlrev_b32_e32 v208, 16, v188
	v_and_b32_e32 v209, 0xffff0000, v188
	v_lshlrev_b32_e32 v188, 16, v189
	v_and_b32_e32 v189, 0xffff0000, v189
	v_pk_add_f32 v[144:145], v[144:145], v[186:187]
	v_pk_add_f32 v[142:143], v[142:143], v[206:207]
	v_pk_add_f32 v[186:187], v[140:141], v[188:189]
	v_pk_add_f32 v[188:189], v[138:139], v[208:209]
	v_cvt_pk_bf16_f32 v138, v142, v143
	v_cvt_pk_bf16_f32 v139, v144, v145
	s_nop 0
	v_cvt_pk_bf16_f32 v140, v188, v189
	v_cvt_pk_bf16_f32 v141, v186, v187
	v_mov_b32_e32 v244, v138
	v_mov_b32_e32 v245, v139
	v_mov_b32_e32 v246, v140
	v_mov_b32_e32 v247, v141
	s_nop 1
	v_mul_f32_e32 v138, v143, v143
	v_mul_f32_e32 v139, v145, v145
	v_fmac_f32_e32 v138, v142, v142
	v_fmac_f32_e32 v139, v144, v144
	v_add_f32_e32 v138, v138, v139
	v_mul_f32_e32 v139, v189, v189
	v_fmac_f32_e32 v139, v188, v188
	v_add_f32_e32 v138, v139, v138
	v_mul_f32_e32 v139, v187, v187
	v_fmac_f32_e32 v139, v186, v186
	v_add_f32_e32 v186, v139, v138
	v_lshlrev_b32_e32 v138, 16, v190
	v_and_b32_e32 v139, 0xffff0000, v190
	v_lshlrev_b32_e32 v140, 16, v191
	v_and_b32_e32 v141, 0xffff0000, v191
	v_lshlrev_b32_e32 v142, 16, v192
	v_and_b32_e32 v143, 0xffff0000, v192
	v_lshlrev_b32_e32 v144, 16, v193
	v_and_b32_e32 v145, 0xffff0000, v193
	v_pk_add_f32 v[132:133], v[132:133], v[140:141]
	v_pk_add_f32 v[130:131], v[130:131], v[138:139]
	v_pk_add_f32 v[140:141], v[126:127], v[142:143]
	v_cvt_pk_bf16_f32 v126, v130, v131
	v_cvt_pk_bf16_f32 v127, v132, v133
	v_pk_add_f32 v[138:139], v[128:129], v[144:145]
	v_cvt_pk_bf16_f32 v128, v140, v141
	s_nop 0
	v_cvt_pk_bf16_f32 v129, v138, v139
	v_mov_b32_dpp v252, v244 row_ror:8 row_mask:0xf bank_mask:0xf
	v_mov_b32_dpp v226, v126 row_ror:8 row_mask:0xf bank_mask:0xf
	v_cndmask_b32_e64 v126, v126, v252, s[98:99]
	v_cndmask_b32_e64 v244, v226, v244, s[98:99]
	v_mov_b32_dpp v252, v245 row_ror:8 row_mask:0xf bank_mask:0xf
	v_mov_b32_dpp v226, v127 row_ror:8 row_mask:0xf bank_mask:0xf
	v_cndmask_b32_e64 v127, v127, v252, s[98:99]
	v_cndmask_b32_e64 v245, v226, v245, s[98:99]
	v_mov_b32_dpp v252, v246 row_ror:8 row_mask:0xf bank_mask:0xf
	v_mov_b32_dpp v226, v128 row_ror:8 row_mask:0xf bank_mask:0xf
	v_cndmask_b32_e64 v128, v128, v252, s[98:99]
	v_cndmask_b32_e64 v246, v226, v246, s[98:99]
	v_mov_b32_dpp v252, v247 row_ror:8 row_mask:0xf bank_mask:0xf
	v_mov_b32_dpp v226, v129 row_ror:8 row_mask:0xf bank_mask:0xf
	v_cndmask_b32_e64 v129, v129, v252, s[98:99]
	v_cndmask_b32_e64 v247, v226, v247, s[98:99]
	v_lshl_add_u64 v[240:241], v[202:203], 0, v[250:251]
	v_lshl_add_u64 v[242:243], v[240:241], 0, s[100:101]
	flat_store_dwordx4 v[240:241], v[244:247]
	flat_store_dwordx4 v[242:243], v[126:129]
	s_nop 1
	v_mul_f32_e32 v126, v131, v131
	v_mul_f32_e32 v127, v133, v133
	v_fmac_f32_e32 v126, v130, v130
	v_fmac_f32_e32 v127, v132, v132
	v_add_f32_e32 v126, v126, v127
	v_mul_f32_e32 v127, v141, v141
	v_fmac_f32_e32 v127, v140, v140
	v_add_f32_e32 v126, v127, v126
	v_mul_f32_e32 v127, v139, v139
	v_fmac_f32_e32 v127, v138, v138
	v_add_f32_e32 v126, v127, v126
	v_and_b32_e32 v128, 64, v228
	v_add_f32_e32 v127, v186, v126
	v_xor_b32_e32 v126, 16, v228
	v_add_u32_e32 v129, 64, v128
	v_cmp_lt_i32_e32 vcc, v126, v129
	s_nop 1
	v_cndmask_b32_e32 v126, v228, v126, vcc
	v_lshlrev_b32_e32 v126, 2, v126
	ds_bpermute_b32 v128, v126, v127
	s_waitcnt lgkmcnt(0)
	v_add_f32_e32 v128, v127, v128
	v_xor_b32_e32 v127, 32, v228
	v_cmp_lt_i32_e32 vcc, v127, v129
	s_nop 1
	v_cndmask_b32_e32 v127, v228, v127, vcc
	v_lshlrev_b32_e32 v127, 2, v127
	ds_bpermute_b32 v129, v127, v128
	s_and_saveexec_b64 s[12:13], s[40:41]
	s_cbranch_execz .LBB0_486
	v_lshl_add_u64 v[130:131], v[168:169], 2, s[4:5]
	s_waitcnt lgkmcnt(0)
	v_add_f32_e32 v128, v128, v129
	flat_atomic_add_f32 v[130:131], v128
.LBB0_486:
	s_or_b64 exec, exec, s[12:13]
	v_lshlrev_b32_e32 v128, 16, v150
	s_waitcnt lgkmcnt(0)
	v_and_b32_e32 v129, 0xffff0000, v150
	v_lshlrev_b32_e32 v130, 16, v151
	v_and_b32_e32 v131, 0xffff0000, v151
	v_lshlrev_b32_e32 v132, 16, v152
	v_and_b32_e32 v133, 0xffff0000, v152
	v_pk_add_f32 v[110:111], v[110:111], v[128:129]
	v_pk_add_f32 v[112:113], v[112:113], v[130:131]
	v_pk_add_f32 v[130:131], v[106:107], v[132:133]
	v_cvt_pk_bf16_f32 v106, v110, v111
	v_mul_f32_e32 v111, v111, v111
	v_fmac_f32_e32 v111, v110, v110
	v_mul_f32_e32 v110, v113, v113
	v_fmac_f32_e32 v110, v112, v112
	v_lshlrev_b32_e32 v138, 16, v153
	v_and_b32_e32 v139, 0xffff0000, v153
	v_add_f32_e32 v110, v111, v110
	v_mul_f32_e32 v111, v131, v131
	v_pk_add_f32 v[128:129], v[108:109], v[138:139]
	v_fmac_f32_e32 v111, v130, v130
	v_add_f32_e32 v110, v111, v110
	v_mul_f32_e32 v111, v129, v129
	v_fmac_f32_e32 v111, v128, v128
	v_cvt_pk_bf16_f32 v107, v112, v113
	v_add_f32_e32 v132, v111, v110
	v_lshlrev_b32_e32 v110, 16, v146
	v_and_b32_e32 v111, 0xffff0000, v146
	v_lshlrev_b32_e32 v112, 16, v147
	v_and_b32_e32 v113, 0xffff0000, v147
	v_cvt_pk_bf16_f32 v108, v130, v131
	v_cvt_pk_bf16_f32 v109, v128, v129
	v_lshlrev_b32_e32 v128, 16, v148
	v_and_b32_e32 v129, 0xffff0000, v148
	v_pk_add_f32 v[104:105], v[104:105], v[112:113]
	v_pk_add_f32 v[102:103], v[102:103], v[110:111]
	v_pk_add_f32 v[112:113], v[98:99], v[128:129]
	v_mul_f32_e32 v98, v103, v103
	v_mul_f32_e32 v99, v105, v105
	v_fmac_f32_e32 v98, v102, v102
	v_fmac_f32_e32 v99, v104, v104
	v_lshlrev_b32_e32 v130, 16, v149
	v_and_b32_e32 v131, 0xffff0000, v149
	v_add_f32_e32 v98, v98, v99
	v_mul_f32_e32 v99, v113, v113
	v_pk_add_f32 v[110:111], v[100:101], v[130:131]
	v_fmac_f32_e32 v99, v112, v112
	v_add_f32_e32 v98, v99, v98
	v_mul_f32_e32 v99, v111, v111
	v_fmac_f32_e32 v99, v110, v110
	v_add_f32_e32 v98, v99, v98
	v_add_f32_e32 v101, v132, v98
	ds_bpermute_b32 v130, v126, v101
	v_lshl_add_u64 v[98:99], s[46:47], 0, v[180:181]
	v_lshl_add_u64 v[128:129], v[164:165], 1, v[98:99]
	v_mov_b32_e32 v244, v106
	v_mov_b32_e32 v245, v107
	v_mov_b32_e32 v246, v108
	v_mov_b32_e32 v247, v109
	v_cvt_pk_bf16_f32 v100, v102, v103
	s_waitcnt lgkmcnt(0)
	v_add_f32_e32 v98, v101, v130
	ds_bpermute_b32 v99, v127, v98
	v_cvt_pk_bf16_f32 v101, v104, v105
	v_cvt_pk_bf16_f32 v102, v112, v113
	v_cvt_pk_bf16_f32 v103, v110, v111
	v_mov_b32_dpp v252, v244 row_ror:8 row_mask:0xf bank_mask:0xf
	v_mov_b32_dpp v226, v100 row_ror:8 row_mask:0xf bank_mask:0xf
	v_cndmask_b32_e64 v100, v100, v252, s[98:99]
	v_cndmask_b32_e64 v244, v226, v244, s[98:99]
	v_mov_b32_dpp v252, v245 row_ror:8 row_mask:0xf bank_mask:0xf
	v_mov_b32_dpp v226, v101 row_ror:8 row_mask:0xf bank_mask:0xf
	v_cndmask_b32_e64 v101, v101, v252, s[98:99]
	v_cndmask_b32_e64 v245, v226, v245, s[98:99]
	v_mov_b32_dpp v252, v246 row_ror:8 row_mask:0xf bank_mask:0xf
	v_mov_b32_dpp v226, v102 row_ror:8 row_mask:0xf bank_mask:0xf
	v_cndmask_b32_e64 v102, v102, v252, s[98:99]
	v_cndmask_b32_e64 v246, v226, v246, s[98:99]
	v_mov_b32_dpp v252, v247 row_ror:8 row_mask:0xf bank_mask:0xf
	v_mov_b32_dpp v226, v103 row_ror:8 row_mask:0xf bank_mask:0xf
	v_cndmask_b32_e64 v103, v103, v252, s[98:99]
	v_cndmask_b32_e64 v247, v226, v247, s[98:99]
	v_lshl_add_u64 v[240:241], v[128:129], 0, v[250:251]
	v_lshl_add_u64 v[242:243], v[240:241], 0, s[100:101]
	flat_store_dwordx4 v[240:241], v[244:247]
	flat_store_dwordx4 v[242:243], v[100:103]
	s_and_saveexec_b64 s[12:13], s[40:41]
	s_cbranch_execz .LBB0_488
	v_lshl_add_u64 v[100:101], v[178:179], 2, s[4:5]
	s_waitcnt lgkmcnt(0)
	v_add_f32_e32 v98, v98, v99
	flat_atomic_add_f32 v[100:101], v98
.LBB0_488:
	s_or_b64 exec, exec, s[12:13]
	v_lshlrev_b32_e32 v98, 16, v134
	s_waitcnt lgkmcnt(0)
	v_and_b32_e32 v99, 0xffff0000, v134
	v_lshlrev_b32_e32 v100, 16, v135
	v_and_b32_e32 v101, 0xffff0000, v135
	v_lshlrev_b32_e32 v102, 16, v136
	v_and_b32_e32 v103, 0xffff0000, v136
	v_pk_add_f32 v[94:95], v[94:95], v[98:99]
	v_pk_add_f32 v[96:97], v[96:97], v[100:101]
	v_pk_add_f32 v[100:101], v[90:91], v[102:103]
	v_cvt_pk_bf16_f32 v90, v94, v95
	v_mul_f32_e32 v95, v95, v95
	v_fmac_f32_e32 v95, v94, v94
	v_mul_f32_e32 v94, v97, v97
	v_fmac_f32_e32 v94, v96, v96
	v_lshlrev_b32_e32 v104, 16, v137
	v_and_b32_e32 v105, 0xffff0000, v137
	v_add_f32_e32 v94, v95, v94
	v_mul_f32_e32 v95, v101, v101
	v_pk_add_f32 v[98:99], v[92:93], v[104:105]
	v_fmac_f32_e32 v95, v100, v100
	v_add_f32_e32 v94, v95, v94
	v_mul_f32_e32 v95, v99, v99
	v_fmac_f32_e32 v95, v98, v98
	v_cvt_pk_bf16_f32 v91, v96, v97
	v_add_f32_e32 v102, v95, v94
	v_lshlrev_b32_e32 v94, 16, v122
	v_and_b32_e32 v95, 0xffff0000, v122
	v_lshlrev_b32_e32 v96, 16, v123
	v_and_b32_e32 v97, 0xffff0000, v123
	v_cvt_pk_bf16_f32 v92, v100, v101
	v_cvt_pk_bf16_f32 v93, v98, v99
	v_lshlrev_b32_e32 v98, 16, v124
	v_and_b32_e32 v99, 0xffff0000, v124
	v_pk_add_f32 v[88:89], v[88:89], v[96:97]
	v_pk_add_f32 v[86:87], v[86:87], v[94:95]
	v_pk_add_f32 v[96:97], v[82:83], v[98:99]
	v_mul_f32_e32 v82, v87, v87
	v_mul_f32_e32 v83, v89, v89
	v_fmac_f32_e32 v82, v86, v86
	v_fmac_f32_e32 v83, v88, v88
	v_lshlrev_b32_e32 v100, 16, v125
	v_and_b32_e32 v101, 0xffff0000, v125
	v_add_f32_e32 v82, v82, v83
	v_mul_f32_e32 v83, v97, v97
	v_pk_add_f32 v[94:95], v[84:85], v[100:101]
	v_fmac_f32_e32 v83, v96, v96
	v_add_f32_e32 v82, v83, v82
	v_mul_f32_e32 v83, v95, v95
	v_fmac_f32_e32 v83, v94, v94
	v_add_f32_e32 v82, v83, v82
	v_add_f32_e32 v85, v102, v82
	ds_bpermute_b32 v100, v126, v85
	v_lshl_add_u64 v[82:83], s[46:47], 0, v[176:177]
	v_lshl_add_u64 v[98:99], v[164:165], 1, v[82:83]
	v_mov_b32_e32 v244, v90
	v_mov_b32_e32 v245, v91
	v_mov_b32_e32 v246, v92
	v_mov_b32_e32 v247, v93
	v_cvt_pk_bf16_f32 v84, v86, v87
	s_waitcnt lgkmcnt(0)
	v_add_f32_e32 v82, v85, v100
	ds_bpermute_b32 v83, v127, v82
	v_cvt_pk_bf16_f32 v85, v88, v89
	v_cvt_pk_bf16_f32 v86, v96, v97
	v_cvt_pk_bf16_f32 v87, v94, v95
	v_mov_b32_dpp v252, v244 row_ror:8 row_mask:0xf bank_mask:0xf
	v_mov_b32_dpp v226, v84 row_ror:8 row_mask:0xf bank_mask:0xf
	v_cndmask_b32_e64 v84, v84, v252, s[98:99]
	v_cndmask_b32_e64 v244, v226, v244, s[98:99]
	v_mov_b32_dpp v252, v245 row_ror:8 row_mask:0xf bank_mask:0xf
	v_mov_b32_dpp v226, v85 row_ror:8 row_mask:0xf bank_mask:0xf
	v_cndmask_b32_e64 v85, v85, v252, s[98:99]
	v_cndmask_b32_e64 v245, v226, v245, s[98:99]
	v_mov_b32_dpp v252, v246 row_ror:8 row_mask:0xf bank_mask:0xf
	v_mov_b32_dpp v226, v86 row_ror:8 row_mask:0xf bank_mask:0xf
	v_cndmask_b32_e64 v86, v86, v252, s[98:99]
	v_cndmask_b32_e64 v246, v226, v246, s[98:99]
	v_mov_b32_dpp v252, v247 row_ror:8 row_mask:0xf bank_mask:0xf
	v_mov_b32_dpp v226, v87 row_ror:8 row_mask:0xf bank_mask:0xf
	v_cndmask_b32_e64 v87, v87, v252, s[98:99]
	v_cndmask_b32_e64 v247, v226, v247, s[98:99]
	v_lshl_add_u64 v[240:241], v[98:99], 0, v[250:251]
	v_lshl_add_u64 v[242:243], v[240:241], 0, s[100:101]
	flat_store_dwordx4 v[240:241], v[244:247]
	flat_store_dwordx4 v[242:243], v[84:87]
	s_and_saveexec_b64 s[12:13], s[40:41]
	s_cbranch_execz .LBB0_490
	v_lshl_add_u64 v[84:85], v[174:175], 2, s[4:5]
	s_waitcnt lgkmcnt(0)
	v_add_f32_e32 v82, v82, v83
	flat_atomic_add_f32 v[84:85], v82
.LBB0_490:
	s_or_b64 exec, exec, s[12:13]
	v_lshlrev_b32_e32 v82, 16, v118
	s_waitcnt lgkmcnt(0)
	v_and_b32_e32 v83, 0xffff0000, v118
	v_lshlrev_b32_e32 v84, 16, v119
	v_and_b32_e32 v85, 0xffff0000, v119
	v_lshlrev_b32_e32 v86, 16, v120
	v_and_b32_e32 v87, 0xffff0000, v120
	v_pk_add_f32 v[78:79], v[78:79], v[82:83]
	v_pk_add_f32 v[80:81], v[80:81], v[84:85]
	v_pk_add_f32 v[84:85], v[74:75], v[86:87]
	v_cvt_pk_bf16_f32 v74, v78, v79
	v_mul_f32_e32 v79, v79, v79
	v_fmac_f32_e32 v79, v78, v78
	v_mul_f32_e32 v78, v81, v81
	v_fmac_f32_e32 v78, v80, v80
	v_lshlrev_b32_e32 v88, 16, v121
	v_and_b32_e32 v89, 0xffff0000, v121
	v_add_f32_e32 v78, v79, v78
	v_mul_f32_e32 v79, v85, v85
	v_pk_add_f32 v[82:83], v[76:77], v[88:89]
	v_fmac_f32_e32 v79, v84, v84
	v_add_f32_e32 v78, v79, v78
	v_mul_f32_e32 v79, v83, v83
	v_fmac_f32_e32 v79, v82, v82
	v_cvt_pk_bf16_f32 v75, v80, v81
	v_add_f32_e32 v86, v79, v78
	v_lshlrev_b32_e32 v78, 16, v114
	v_and_b32_e32 v79, 0xffff0000, v114
	v_lshlrev_b32_e32 v80, 16, v115
	v_and_b32_e32 v81, 0xffff0000, v115
	v_cvt_pk_bf16_f32 v76, v84, v85
	v_cvt_pk_bf16_f32 v77, v82, v83
	v_lshlrev_b32_e32 v82, 16, v116
	v_and_b32_e32 v83, 0xffff0000, v116
	v_pk_add_f32 v[72:73], v[72:73], v[80:81]
	v_pk_add_f32 v[70:71], v[70:71], v[78:79]
	v_pk_add_f32 v[80:81], v[66:67], v[82:83]
	v_mul_f32_e32 v66, v71, v71
	v_mul_f32_e32 v67, v73, v73
	v_fmac_f32_e32 v66, v70, v70
	v_fmac_f32_e32 v67, v72, v72
	v_lshlrev_b32_e32 v84, 16, v117
	v_and_b32_e32 v85, 0xffff0000, v117
	v_add_f32_e32 v66, v66, v67
	v_mul_f32_e32 v67, v81, v81
	v_pk_add_f32 v[78:79], v[68:69], v[84:85]
	v_fmac_f32_e32 v67, v80, v80
	v_add_f32_e32 v66, v67, v66
	v_mul_f32_e32 v67, v79, v79
	v_fmac_f32_e32 v67, v78, v78
	v_add_f32_e32 v66, v67, v66
	v_add_f32_e32 v69, v86, v66
	ds_bpermute_b32 v84, v126, v69
	v_lshl_add_u64 v[66:67], s[46:47], 0, v[172:173]
	v_lshl_add_u64 v[82:83], v[164:165], 1, v[66:67]
	v_mov_b32_e32 v244, v74
	v_mov_b32_e32 v245, v75
	v_mov_b32_e32 v246, v76
	v_mov_b32_e32 v247, v77
	v_cvt_pk_bf16_f32 v68, v70, v71
	s_waitcnt lgkmcnt(0)
	v_add_f32_e32 v66, v69, v84
	ds_bpermute_b32 v67, v127, v66
	v_cvt_pk_bf16_f32 v69, v72, v73
	v_cvt_pk_bf16_f32 v70, v80, v81
	v_cvt_pk_bf16_f32 v71, v78, v79
	v_mov_b32_dpp v252, v244 row_ror:8 row_mask:0xf bank_mask:0xf
	v_mov_b32_dpp v226, v68 row_ror:8 row_mask:0xf bank_mask:0xf
	v_cndmask_b32_e64 v68, v68, v252, s[98:99]
	v_cndmask_b32_e64 v244, v226, v244, s[98:99]
	v_mov_b32_dpp v252, v245 row_ror:8 row_mask:0xf bank_mask:0xf
	v_mov_b32_dpp v226, v69 row_ror:8 row_mask:0xf bank_mask:0xf
	v_cndmask_b32_e64 v69, v69, v252, s[98:99]
	v_cndmask_b32_e64 v245, v226, v245, s[98:99]
	v_mov_b32_dpp v252, v246 row_ror:8 row_mask:0xf bank_mask:0xf
	v_mov_b32_dpp v226, v70 row_ror:8 row_mask:0xf bank_mask:0xf
	v_cndmask_b32_e64 v70, v70, v252, s[98:99]
	v_cndmask_b32_e64 v246, v226, v246, s[98:99]
	v_mov_b32_dpp v252, v247 row_ror:8 row_mask:0xf bank_mask:0xf
	v_mov_b32_dpp v226, v71 row_ror:8 row_mask:0xf bank_mask:0xf
	v_cndmask_b32_e64 v71, v71, v252, s[98:99]
	v_cndmask_b32_e64 v247, v226, v247, s[98:99]
	v_lshl_add_u64 v[240:241], v[82:83], 0, v[250:251]
	v_lshl_add_u64 v[242:243], v[240:241], 0, s[100:101]
	flat_store_dwordx4 v[240:241], v[244:247]
	flat_store_dwordx4 v[242:243], v[68:71]
	s_and_saveexec_b64 s[12:13], s[40:41]
	s_cbranch_execz .LBB0_492
	v_lshl_add_u64 v[68:69], v[170:171], 2, s[4:5]
	s_waitcnt lgkmcnt(0)
	v_add_f32_e32 v66, v66, v67
	flat_atomic_add_f32 v[68:69], v66
.LBB0_492:
	s_or_b64 exec, exec, s[12:13]
	v_add_u32_e32 v106, 0x80, v168
	v_ashrrev_i32_e32 v107, 31, v106
	v_lshlrev_b64 v[112:113], 11, v[106:107]
	s_waitcnt lgkmcnt(0)
	v_lshl_add_u64 v[66:67], v[166:167], 0, v[112:113]
	flat_load_dwordx4 v[108:111], v[66:67]
	flat_load_dwordx4 v[90:93], v[66:67] offset:64
	v_add_u32_e32 v102, 0x90, v168
	v_ashrrev_i32_e32 v103, 31, v102
	v_add_u32_e32 v98, 0xa0, v168
	v_lshlrev_b64 v[104:105], 11, v[102:103]
	v_ashrrev_i32_e32 v99, 31, v98
	v_add_u32_e32 v94, 0xb0, v168
	v_lshl_add_u64 v[66:67], v[166:167], 0, v[104:105]
	v_lshlrev_b64 v[100:101], 11, v[98:99]
	v_ashrrev_i32_e32 v95, 31, v94
	flat_load_dwordx4 v[86:89], v[66:67]
	flat_load_dwordx4 v[82:85], v[66:67] offset:64
	v_lshl_add_u64 v[66:67], v[166:167], 0, v[100:101]
	v_lshlrev_b64 v[96:97], 11, v[94:95]
	flat_load_dwordx4 v[78:81], v[66:67]
	flat_load_dwordx4 v[74:77], v[66:67] offset:64
	v_lshl_add_u64 v[66:67], v[166:167], 0, v[96:97]
	flat_load_dwordx4 v[70:73], v[66:67]
	s_nop 0
	flat_load_dwordx4 v[66:69], v[66:67] offset:64
	v_lshl_add_u64 v[112:113], s[46:47], 0, v[112:113]
	v_lshl_add_u64 v[112:113], v[164:165], 1, v[112:113]
	s_waitcnt vmcnt(0) lgkmcnt(0)
	v_lshlrev_b32_e32 v114, 16, v108
	v_and_b32_e32 v115, 0xffff0000, v108
	v_lshlrev_b32_e32 v108, 16, v109
	v_and_b32_e32 v109, 0xffff0000, v109
	v_lshlrev_b32_e32 v116, 16, v110
	v_and_b32_e32 v117, 0xffff0000, v110
	v_lshlrev_b32_e32 v110, 16, v111
	v_and_b32_e32 v111, 0xffff0000, v111
	v_pk_add_f32 v[64:65], v[64:65], v[108:109]
	v_pk_add_f32 v[62:63], v[62:63], v[114:115]
	v_pk_add_f32 v[108:109], v[60:61], v[110:111]
	v_pk_add_f32 v[110:111], v[58:59], v[116:117]
	v_cvt_pk_bf16_f32 v58, v62, v63
	v_cvt_pk_bf16_f32 v59, v64, v65
	s_nop 0
	v_cvt_pk_bf16_f32 v60, v110, v111
	v_cvt_pk_bf16_f32 v61, v108, v109
	v_mov_b32_e32 v244, v58
	v_mov_b32_e32 v245, v59
	v_mov_b32_e32 v246, v60
	v_mov_b32_e32 v247, v61
	s_nop 1
	v_mul_f32_e32 v58, v63, v63
	v_mul_f32_e32 v59, v65, v65
	v_fmac_f32_e32 v58, v62, v62
	v_fmac_f32_e32 v59, v64, v64
	v_add_f32_e32 v58, v58, v59
	v_mul_f32_e32 v59, v111, v111
	v_fmac_f32_e32 v59, v110, v110
	v_add_f32_e32 v58, v59, v58
	v_mul_f32_e32 v59, v109, v109
	v_fmac_f32_e32 v59, v108, v108
	v_add_f32_e32 v108, v59, v58
	v_lshlrev_b32_e32 v58, 16, v90
	v_and_b32_e32 v59, 0xffff0000, v90
	v_lshlrev_b32_e32 v60, 16, v91
	v_and_b32_e32 v61, 0xffff0000, v91
	v_lshlrev_b32_e32 v62, 16, v92
	v_and_b32_e32 v63, 0xffff0000, v92
	v_lshlrev_b32_e32 v64, 16, v93
	v_and_b32_e32 v65, 0xffff0000, v93
	v_pk_add_f32 v[56:57], v[56:57], v[60:61]
	v_pk_add_f32 v[54:55], v[54:55], v[58:59]
	v_pk_add_f32 v[60:61], v[50:51], v[62:63]
	v_cvt_pk_bf16_f32 v50, v54, v55
	v_cvt_pk_bf16_f32 v51, v56, v57
	v_pk_add_f32 v[58:59], v[52:53], v[64:65]
	v_cvt_pk_bf16_f32 v52, v60, v61
	s_nop 0
	v_cvt_pk_bf16_f32 v53, v58, v59
	v_mov_b32_dpp v252, v244 row_ror:8 row_mask:0xf bank_mask:0xf
	v_mov_b32_dpp v226, v50 row_ror:8 row_mask:0xf bank_mask:0xf
	v_cndmask_b32_e64 v50, v50, v252, s[98:99]
	v_cndmask_b32_e64 v244, v226, v244, s[98:99]
	v_mov_b32_dpp v252, v245 row_ror:8 row_mask:0xf bank_mask:0xf
	v_mov_b32_dpp v226, v51 row_ror:8 row_mask:0xf bank_mask:0xf
	v_cndmask_b32_e64 v51, v51, v252, s[98:99]
	v_cndmask_b32_e64 v245, v226, v245, s[98:99]
	v_mov_b32_dpp v252, v246 row_ror:8 row_mask:0xf bank_mask:0xf
	v_mov_b32_dpp v226, v52 row_ror:8 row_mask:0xf bank_mask:0xf
	v_cndmask_b32_e64 v52, v52, v252, s[98:99]
	v_cndmask_b32_e64 v246, v226, v246, s[98:99]
	v_mov_b32_dpp v252, v247 row_ror:8 row_mask:0xf bank_mask:0xf
	v_mov_b32_dpp v226, v53 row_ror:8 row_mask:0xf bank_mask:0xf
	v_cndmask_b32_e64 v53, v53, v252, s[98:99]
	v_cndmask_b32_e64 v247, v226, v247, s[98:99]
	v_lshl_add_u64 v[240:241], v[112:113], 0, v[250:251]
	v_lshl_add_u64 v[242:243], v[240:241], 0, s[100:101]
	flat_store_dwordx4 v[240:241], v[244:247]
	flat_store_dwordx4 v[242:243], v[50:53]
	s_nop 1
	v_mul_f32_e32 v50, v55, v55
	v_mul_f32_e32 v51, v57, v57
	v_fmac_f32_e32 v50, v54, v54
	v_fmac_f32_e32 v51, v56, v56
	v_add_f32_e32 v50, v50, v51
	v_mul_f32_e32 v51, v61, v61
	v_fmac_f32_e32 v51, v60, v60
	v_add_f32_e32 v50, v51, v50
	v_mul_f32_e32 v51, v59, v59
	v_fmac_f32_e32 v51, v58, v58
	v_add_f32_e32 v50, v51, v50
	v_add_f32_e32 v50, v108, v50
	ds_bpermute_b32 v51, v126, v50
	s_waitcnt lgkmcnt(0)
	v_add_f32_e32 v50, v50, v51
	ds_bpermute_b32 v51, v127, v50
	s_and_saveexec_b64 s[12:13], s[40:41]
	s_cbranch_execz .LBB0_494
	v_lshl_add_u64 v[52:53], v[106:107], 2, s[4:5]
	s_waitcnt lgkmcnt(0)
	v_add_f32_e32 v50, v50, v51
	flat_atomic_add_f32 v[52:53], v50
.LBB0_494:
	s_or_b64 exec, exec, s[12:13]
	v_lshlrev_b32_e32 v50, 16, v86
	s_waitcnt lgkmcnt(0)
	v_and_b32_e32 v51, 0xffff0000, v86
	v_lshlrev_b32_e32 v52, 16, v87
	v_and_b32_e32 v53, 0xffff0000, v87
	v_lshlrev_b32_e32 v54, 16, v88
	v_and_b32_e32 v55, 0xffff0000, v88
	v_pk_add_f32 v[46:47], v[46:47], v[50:51]
	v_pk_add_f32 v[48:49], v[48:49], v[52:53]
	v_pk_add_f32 v[52:53], v[42:43], v[54:55]
	v_cvt_pk_bf16_f32 v42, v46, v47
	v_mul_f32_e32 v47, v47, v47
	v_fmac_f32_e32 v47, v46, v46
	v_mul_f32_e32 v46, v49, v49
	v_fmac_f32_e32 v46, v48, v48
	v_lshlrev_b32_e32 v56, 16, v89
	v_and_b32_e32 v57, 0xffff0000, v89
	v_add_f32_e32 v46, v47, v46
	v_mul_f32_e32 v47, v53, v53
	v_pk_add_f32 v[50:51], v[44:45], v[56:57]
	v_fmac_f32_e32 v47, v52, v52
	v_add_f32_e32 v46, v47, v46
	v_mul_f32_e32 v47, v51, v51
	v_fmac_f32_e32 v47, v50, v50
	v_cvt_pk_bf16_f32 v43, v48, v49
	v_add_f32_e32 v54, v47, v46
	v_lshlrev_b32_e32 v46, 16, v82
	v_and_b32_e32 v47, 0xffff0000, v82
	v_lshlrev_b32_e32 v48, 16, v83
	v_and_b32_e32 v49, 0xffff0000, v83
	v_cvt_pk_bf16_f32 v44, v52, v53
	v_cvt_pk_bf16_f32 v45, v50, v51
	v_lshlrev_b32_e32 v50, 16, v84
	v_and_b32_e32 v51, 0xffff0000, v84
	v_pk_add_f32 v[40:41], v[40:41], v[48:49]
	v_pk_add_f32 v[38:39], v[38:39], v[46:47]
	v_pk_add_f32 v[48:49], v[34:35], v[50:51]
	v_mul_f32_e32 v34, v39, v39
	v_mul_f32_e32 v35, v41, v41
	v_fmac_f32_e32 v34, v38, v38
	v_fmac_f32_e32 v35, v40, v40
	v_lshlrev_b32_e32 v52, 16, v85
	v_and_b32_e32 v53, 0xffff0000, v85
	v_add_f32_e32 v34, v34, v35
	v_mul_f32_e32 v35, v49, v49
	v_pk_add_f32 v[46:47], v[36:37], v[52:53]
	v_fmac_f32_e32 v35, v48, v48
	v_add_f32_e32 v34, v35, v34
	v_mul_f32_e32 v35, v47, v47
	v_fmac_f32_e32 v35, v46, v46
	v_add_f32_e32 v34, v35, v34
	v_add_f32_e32 v37, v54, v34
	ds_bpermute_b32 v52, v126, v37
	v_lshl_add_u64 v[34:35], s[46:47], 0, v[104:105]
	v_lshl_add_u64 v[50:51], v[164:165], 1, v[34:35]
	v_mov_b32_e32 v244, v42
	v_mov_b32_e32 v245, v43
	v_mov_b32_e32 v246, v44
	v_mov_b32_e32 v247, v45
	v_cvt_pk_bf16_f32 v36, v38, v39
	s_waitcnt lgkmcnt(0)
	v_add_f32_e32 v34, v37, v52
	ds_bpermute_b32 v35, v127, v34
	v_cvt_pk_bf16_f32 v37, v40, v41
	v_cvt_pk_bf16_f32 v38, v48, v49
	v_cvt_pk_bf16_f32 v39, v46, v47
	v_mov_b32_dpp v252, v244 row_ror:8 row_mask:0xf bank_mask:0xf
	v_mov_b32_dpp v226, v36 row_ror:8 row_mask:0xf bank_mask:0xf
	v_cndmask_b32_e64 v36, v36, v252, s[98:99]
	v_cndmask_b32_e64 v244, v226, v244, s[98:99]
	v_mov_b32_dpp v252, v245 row_ror:8 row_mask:0xf bank_mask:0xf
	v_mov_b32_dpp v226, v37 row_ror:8 row_mask:0xf bank_mask:0xf
	v_cndmask_b32_e64 v37, v37, v252, s[98:99]
	v_cndmask_b32_e64 v245, v226, v245, s[98:99]
	v_mov_b32_dpp v252, v246 row_ror:8 row_mask:0xf bank_mask:0xf
	v_mov_b32_dpp v226, v38 row_ror:8 row_mask:0xf bank_mask:0xf
	v_cndmask_b32_e64 v38, v38, v252, s[98:99]
	v_cndmask_b32_e64 v246, v226, v246, s[98:99]
	v_mov_b32_dpp v252, v247 row_ror:8 row_mask:0xf bank_mask:0xf
	v_mov_b32_dpp v226, v39 row_ror:8 row_mask:0xf bank_mask:0xf
	v_cndmask_b32_e64 v39, v39, v252, s[98:99]
	v_cndmask_b32_e64 v247, v226, v247, s[98:99]
	v_lshl_add_u64 v[240:241], v[50:51], 0, v[250:251]
	v_lshl_add_u64 v[242:243], v[240:241], 0, s[100:101]
	flat_store_dwordx4 v[240:241], v[244:247]
	flat_store_dwordx4 v[242:243], v[36:39]
	s_and_saveexec_b64 s[12:13], s[40:41]
	s_cbranch_execz .LBB0_496
	v_lshl_add_u64 v[36:37], v[102:103], 2, s[4:5]
	s_waitcnt lgkmcnt(0)
	v_add_f32_e32 v34, v34, v35
	flat_atomic_add_f32 v[36:37], v34
.LBB0_496:
	s_or_b64 exec, exec, s[12:13]
	v_lshlrev_b32_e32 v34, 16, v78
	s_waitcnt lgkmcnt(0)
	v_and_b32_e32 v35, 0xffff0000, v78
	v_lshlrev_b32_e32 v36, 16, v79
	v_and_b32_e32 v37, 0xffff0000, v79
	v_lshlrev_b32_e32 v38, 16, v80
	v_and_b32_e32 v39, 0xffff0000, v80
	v_pk_add_f32 v[30:31], v[30:31], v[34:35]
	v_pk_add_f32 v[32:33], v[32:33], v[36:37]
	v_pk_add_f32 v[36:37], v[26:27], v[38:39]
	v_cvt_pk_bf16_f32 v26, v30, v31
	v_mul_f32_e32 v31, v31, v31
	v_fmac_f32_e32 v31, v30, v30
	v_mul_f32_e32 v30, v33, v33
	v_fmac_f32_e32 v30, v32, v32
	v_lshlrev_b32_e32 v40, 16, v81
	v_and_b32_e32 v41, 0xffff0000, v81
	v_add_f32_e32 v30, v31, v30
	v_mul_f32_e32 v31, v37, v37
	v_pk_add_f32 v[34:35], v[28:29], v[40:41]
	v_fmac_f32_e32 v31, v36, v36
	v_add_f32_e32 v30, v31, v30
	v_mul_f32_e32 v31, v35, v35
	v_fmac_f32_e32 v31, v34, v34
	v_cvt_pk_bf16_f32 v27, v32, v33
	v_add_f32_e32 v38, v31, v30
	v_lshlrev_b32_e32 v30, 16, v74
	v_and_b32_e32 v31, 0xffff0000, v74
	v_lshlrev_b32_e32 v32, 16, v75
	v_and_b32_e32 v33, 0xffff0000, v75
	v_cvt_pk_bf16_f32 v28, v36, v37
	v_cvt_pk_bf16_f32 v29, v34, v35
	v_lshlrev_b32_e32 v34, 16, v76
	v_and_b32_e32 v35, 0xffff0000, v76
	v_pk_add_f32 v[24:25], v[24:25], v[32:33]
	v_pk_add_f32 v[22:23], v[22:23], v[30:31]
	v_pk_add_f32 v[32:33], v[18:19], v[34:35]
	v_mul_f32_e32 v18, v23, v23
	v_mul_f32_e32 v19, v25, v25
	v_fmac_f32_e32 v18, v22, v22
	v_fmac_f32_e32 v19, v24, v24
	v_lshlrev_b32_e32 v36, 16, v77
	v_and_b32_e32 v37, 0xffff0000, v77
	v_add_f32_e32 v18, v18, v19
	v_mul_f32_e32 v19, v33, v33
	v_pk_add_f32 v[30:31], v[20:21], v[36:37]
	v_fmac_f32_e32 v19, v32, v32
	v_add_f32_e32 v18, v19, v18
	v_mul_f32_e32 v19, v31, v31
	v_fmac_f32_e32 v19, v30, v30
	v_add_f32_e32 v18, v19, v18
	v_add_f32_e32 v21, v38, v18
	ds_bpermute_b32 v36, v126, v21
	v_lshl_add_u64 v[18:19], s[46:47], 0, v[100:101]
	v_lshl_add_u64 v[34:35], v[164:165], 1, v[18:19]
	v_mov_b32_e32 v244, v26
	v_mov_b32_e32 v245, v27
	v_mov_b32_e32 v246, v28
	v_mov_b32_e32 v247, v29
	v_cvt_pk_bf16_f32 v20, v22, v23
	s_waitcnt lgkmcnt(0)
	v_add_f32_e32 v18, v21, v36
	ds_bpermute_b32 v19, v127, v18
	v_cvt_pk_bf16_f32 v21, v24, v25
	v_cvt_pk_bf16_f32 v22, v32, v33
	v_cvt_pk_bf16_f32 v23, v30, v31
	v_mov_b32_dpp v252, v244 row_ror:8 row_mask:0xf bank_mask:0xf
	v_mov_b32_dpp v226, v20 row_ror:8 row_mask:0xf bank_mask:0xf
	v_cndmask_b32_e64 v20, v20, v252, s[98:99]
	v_cndmask_b32_e64 v244, v226, v244, s[98:99]
	v_mov_b32_dpp v252, v245 row_ror:8 row_mask:0xf bank_mask:0xf
	v_mov_b32_dpp v226, v21 row_ror:8 row_mask:0xf bank_mask:0xf
	v_cndmask_b32_e64 v21, v21, v252, s[98:99]
	v_cndmask_b32_e64 v245, v226, v245, s[98:99]
	v_mov_b32_dpp v252, v246 row_ror:8 row_mask:0xf bank_mask:0xf
	v_mov_b32_dpp v226, v22 row_ror:8 row_mask:0xf bank_mask:0xf
	v_cndmask_b32_e64 v22, v22, v252, s[98:99]
	v_cndmask_b32_e64 v246, v226, v246, s[98:99]
	v_mov_b32_dpp v252, v247 row_ror:8 row_mask:0xf bank_mask:0xf
	v_mov_b32_dpp v226, v23 row_ror:8 row_mask:0xf bank_mask:0xf
	v_cndmask_b32_e64 v23, v23, v252, s[98:99]
	v_cndmask_b32_e64 v247, v226, v247, s[98:99]
	v_lshl_add_u64 v[240:241], v[34:35], 0, v[250:251]
	v_lshl_add_u64 v[242:243], v[240:241], 0, s[100:101]
	flat_store_dwordx4 v[240:241], v[244:247]
	flat_store_dwordx4 v[242:243], v[20:23]
	s_and_saveexec_b64 s[12:13], s[40:41]
	s_cbranch_execz .LBB0_498
	v_lshl_add_u64 v[20:21], v[98:99], 2, s[4:5]
	s_waitcnt lgkmcnt(0)
	v_add_f32_e32 v18, v18, v19
	flat_atomic_add_f32 v[20:21], v18
.LBB0_498:
	s_or_b64 exec, exec, s[12:13]
	v_lshlrev_b32_e32 v18, 16, v70
	s_waitcnt lgkmcnt(0)
	v_and_b32_e32 v19, 0xffff0000, v70
	v_lshlrev_b32_e32 v20, 16, v71
	v_and_b32_e32 v21, 0xffff0000, v71
	v_lshlrev_b32_e32 v22, 16, v72
	v_and_b32_e32 v23, 0xffff0000, v72
	v_pk_add_f32 v[14:15], v[14:15], v[18:19]
	v_pk_add_f32 v[16:17], v[16:17], v[20:21]
	v_pk_add_f32 v[20:21], v[10:11], v[22:23]
	v_cvt_pk_bf16_f32 v10, v14, v15
	v_mul_f32_e32 v15, v15, v15
	v_fmac_f32_e32 v15, v14, v14
	v_mul_f32_e32 v14, v17, v17
	v_fmac_f32_e32 v14, v16, v16
	v_lshlrev_b32_e32 v24, 16, v73
	v_and_b32_e32 v25, 0xffff0000, v73
	v_add_f32_e32 v14, v15, v14
	v_mul_f32_e32 v15, v21, v21
	v_pk_add_f32 v[18:19], v[12:13], v[24:25]
	v_fmac_f32_e32 v15, v20, v20
	v_add_f32_e32 v14, v15, v14
	v_mul_f32_e32 v15, v19, v19
	v_fmac_f32_e32 v15, v18, v18
	v_cvt_pk_bf16_f32 v11, v16, v17
	v_add_f32_e32 v22, v15, v14
	v_lshlrev_b32_e32 v14, 16, v66
	v_and_b32_e32 v15, 0xffff0000, v66
	v_lshlrev_b32_e32 v16, 16, v67
	v_and_b32_e32 v17, 0xffff0000, v67
	v_cvt_pk_bf16_f32 v12, v20, v21
	v_cvt_pk_bf16_f32 v13, v18, v19
	v_lshlrev_b32_e32 v18, 16, v68
	v_and_b32_e32 v19, 0xffff0000, v68
	v_pk_add_f32 v[8:9], v[8:9], v[16:17]
	v_pk_add_f32 v[6:7], v[6:7], v[14:15]
	v_pk_add_f32 v[16:17], v[2:3], v[18:19]
	v_mul_f32_e32 v2, v7, v7
	v_mul_f32_e32 v3, v9, v9
	v_fmac_f32_e32 v2, v6, v6
	v_fmac_f32_e32 v3, v8, v8
	v_lshlrev_b32_e32 v20, 16, v69
	v_and_b32_e32 v21, 0xffff0000, v69
	v_add_f32_e32 v2, v2, v3
	v_mul_f32_e32 v3, v17, v17
	v_pk_add_f32 v[14:15], v[4:5], v[20:21]
	v_fmac_f32_e32 v3, v16, v16
	v_add_f32_e32 v2, v3, v2
	v_mul_f32_e32 v3, v15, v15
	v_fmac_f32_e32 v3, v14, v14
	v_add_f32_e32 v2, v3, v2
	v_add_f32_e32 v5, v22, v2
	ds_bpermute_b32 v20, v126, v5
	v_lshl_add_u64 v[2:3], s[46:47], 0, v[96:97]
	v_lshl_add_u64 v[18:19], v[164:165], 1, v[2:3]
	v_mov_b32_e32 v244, v10
	v_mov_b32_e32 v245, v11
	v_mov_b32_e32 v246, v12
	v_mov_b32_e32 v247, v13
	v_cvt_pk_bf16_f32 v4, v6, v7
	s_waitcnt lgkmcnt(0)
	v_add_f32_e32 v2, v5, v20
	ds_bpermute_b32 v3, v127, v2
	v_cvt_pk_bf16_f32 v5, v8, v9
	v_cvt_pk_bf16_f32 v6, v16, v17
	v_cvt_pk_bf16_f32 v7, v14, v15
	v_mov_b32_dpp v252, v244 row_ror:8 row_mask:0xf bank_mask:0xf
	v_mov_b32_dpp v226, v4 row_ror:8 row_mask:0xf bank_mask:0xf
	v_cndmask_b32_e64 v4, v4, v252, s[98:99]
	v_cndmask_b32_e64 v244, v226, v244, s[98:99]
	v_mov_b32_dpp v252, v245 row_ror:8 row_mask:0xf bank_mask:0xf
	v_mov_b32_dpp v226, v5 row_ror:8 row_mask:0xf bank_mask:0xf
	v_cndmask_b32_e64 v5, v5, v252, s[98:99]
	v_cndmask_b32_e64 v245, v226, v245, s[98:99]
	v_mov_b32_dpp v252, v246 row_ror:8 row_mask:0xf bank_mask:0xf
	v_mov_b32_dpp v226, v6 row_ror:8 row_mask:0xf bank_mask:0xf
	v_cndmask_b32_e64 v6, v6, v252, s[98:99]
	v_cndmask_b32_e64 v246, v226, v246, s[98:99]
	v_mov_b32_dpp v252, v247 row_ror:8 row_mask:0xf bank_mask:0xf
	v_mov_b32_dpp v226, v7 row_ror:8 row_mask:0xf bank_mask:0xf
	v_cndmask_b32_e64 v7, v7, v252, s[98:99]
	v_cndmask_b32_e64 v247, v226, v247, s[98:99]
	v_lshl_add_u64 v[240:241], v[18:19], 0, v[250:251]
	v_lshl_add_u64 v[242:243], v[240:241], 0, s[100:101]
	flat_store_dwordx4 v[240:241], v[244:247]
	flat_store_dwordx4 v[242:243], v[4:7]
	s_and_saveexec_b64 s[12:13], s[40:41]
	s_cbranch_execz .LBB0_500
	v_lshl_add_u64 v[4:5], v[94:95], 2, s[4:5]
	s_waitcnt lgkmcnt(0)
	v_add_f32_e32 v2, v2, v3
	flat_atomic_add_f32 v[4:5], v2

.LBB0_613:
	s_or_b64 exec, exec, s[4:5]
	v_readlane_b32 s4, v254, 42
	v_readlane_b32 s5, v254, 43
	s_add_u32 s0, s4, s6
	v_readlane_b32 s14, v254, 36
	s_addc_u32 s4, s5, s7
	v_readlane_b32 s15, v254, 37
	s_add_u32 s18, s0, 0x80000
	s_mov_b32 s15, s1
	s_addc_u32 s19, s4, 0
	s_mov_b64 s[12:13], s[82:83]
	s_mov_b64 s[4:5], s[82:83]
	v_writelane_b32 v254, s14, 36
	s_mov_b64 s[42:43], s[82:83]
	s_mov_b64 s[40:41], s[82:83]
	v_mov_b32_e32 v16, v224
	s_waitcnt lgkmcnt(0)
	s_barrier
	v_writelane_b32 v254, s15, 37
	s_and_b64 vcc, exec, s[38:39]
	v_readfirstlane_b32 s20, v16
	s_cbranch_vccnz .LBB0_649
	v_lshlrev_b32_e32 v0, 4, v16
	v_add_u32_e32 v2, 0x2000, v0
	v_ashrrev_i32_e32 v3, 31, v2
	v_lshrrev_b32_e32 v3, 22, v3
	v_add_u32_e32 v3, v2, v3
	v_ashrrev_i32_e32 v10, 10, v3
	v_mul_i32_i24_e32 v3, 0x400, v10
	v_sub_u32_e32 v2, v2, v3
	v_lshrrev_b32_e32 v3, 4, v2
	s_add_u32 s0, s12, 0x18000000
	v_bitop3_b32 v2, v3, v2, 32 bitop3:0x6c
	s_addc_u32 s17, s13, 0
	v_readlane_b32 s12, v254, 36
	v_ashrrev_i32_e32 v3, 31, v2
	v_readlane_b32 s13, v254, 37
	v_lshrrev_b32_e32 v3, 26, v3
	s_lshl_b64 s[12:13], s[12:13], 23
	v_add_u32_e32 v3, v2, v3
	v_lshlrev_b32_e32 v4, 3, v10
	s_add_u32 s4, s4, s12
	v_ashrrev_i32_e32 v11, 6, v3
	v_and_b32_e32 v4, -16, v4
	s_addc_u32 s5, s5, s13
	v_add_u32_e32 v4, v11, v4
	s_add_u32 s60, s4, 0x2400000
	v_and_b32_e32 v5, 3, v11
	s_mov_b32 s4, 0x7ffe0
	v_lshrrev_b32_e32 v6, 2, v4
	v_lshlrev_b32_e32 v7, 1, v4
	v_and_or_b32 v5, v4, s4, v5
	v_and_b32_e32 v6, 4, v6
	v_and_b32_e32 v7, 24, v7
	v_and_b32_e32 v3, 0xc0, v3
	v_or3_b32 v5, v5, v6, v7
	v_sub_u32_e32 v2, v2, v3
	v_mov_b32_e32 v7, 1
	v_lshlrev_b32_e32 v6, 5, v10
	v_ashrrev_i16_sdwa v2, v7, sext(v2) dst_sel:DWORD dst_unused:UNUSED_PAD src0_sel:DWORD src1_sel:BYTE_0
	v_and_b32_e32 v6, 32, v6
	v_bfe_i32 v12, v2, 0, 16
	v_add_lshl_u32 v2, v6, v12, 1
	s_waitcnt vmcnt(0)
	v_lshl_add_u32 v154, v5, 13, v2
	v_lshl_add_u32 v156, v4, 13, v2
	v_bfe_i32 v2, v16, 27, 1
	v_lshrrev_b32_e32 v2, 22, v2
	v_add_u32_e32 v2, v0, v2
	v_and_b32_e32 v2, 0xfffffc00, v2
	v_sub_u32_e32 v0, v0, v2
	v_lshrrev_b32_e32 v2, 4, v0
	v_ashrrev_i32_e32 v3, 31, v16
	v_bitop3_b32 v0, v2, v0, 32 bitop3:0x6c
	v_lshrrev_b32_e32 v3, 26, v3
	v_ashrrev_i32_e32 v2, 31, v0
	v_add_u32_e32 v3, v16, v3
	v_lshrrev_b32_e32 v2, 26, v2
	v_ashrrev_i32_e32 v14, 6, v3
	v_add_u32_e32 v2, v0, v2
	v_lshlrev_b32_e32 v3, 3, v14
	v_ashrrev_i32_e32 v13, 6, v2
	v_and_b32_e32 v3, -16, v3
	v_add_u32_e32 v3, v13, v3
	v_and_b32_e32 v4, 3, v13
	v_lshrrev_b32_e32 v5, 2, v3
	v_lshlrev_b32_e32 v6, 1, v3
	v_and_b32_e32 v2, 0xc0, v2
	s_addc_u32 s61, s5, 0
	s_ashr_i32 s21, s20, 6
	v_and_or_b32 v4, v3, s4, v4
	v_and_b32_e32 v5, 4, v5
	v_and_b32_e32 v6, 24, v6
	v_sub_u32_e32 v0, v0, v2
	s_ashr_i32 s28, s20, 8
	s_lshl_b32 s62, s21, 10
	v_or3_b32 v4, v4, v5, v6
	v_lshlrev_b32_e32 v5, 5, v14
	v_ashrrev_i16_sdwa v0, v7, sext(v0) dst_sel:DWORD dst_unused:UNUSED_PAD src0_sel:DWORD src1_sel:BYTE_0
	v_readlane_b32 s4, v254, 17
	v_and_b32_e32 v5, 32, v5
	v_bfe_i32 v15, v0, 0, 16
	v_readlane_b32 s5, v254, 18
	s_add_u32 s12, s60, s4
	v_add_lshl_u32 v2, v5, v15, 1
	s_addc_u32 s13, s61, s5
	s_add_i32 s63, s62, 0
	v_lshl_add_u32 v0, v4, 13, v2
	v_lshrrev_b32_e32 v248, 8, v224
	v_lshl_add_u32 v0, v248, 18, v0
	v_lshl_add_u32 v154, v248, 18, v154
	v_add_u32_e32 v154, 0x80000, v154
	s_add_i32 m0, s63, 0x10000
	v_lshl_add_u32 v158, v3, 13, v2
	global_load_lds_dwordx4 v0, s[12:13]
	s_add_i32 m0, s63, 0x12000
	s_add_u32 s4, s12, 0x40000
	global_load_lds_dwordx4 v154, s[12:13]
	s_addc_u32 s5, s13, 0
	s_add_i32 m0, s63, 0x14000
	v_mov_b32_e32 v155, v1
	global_load_lds_dwordx4 v0, s[4:5]
	s_add_i32 m0, s63, 0x16000
	v_mov_b32_e32 v159, v1
	global_load_lds_dwordx4 v154, s[4:5]
	v_readlane_b32 s4, v254, 13
	s_xor_b32 s4, s4, 0x3000000
	v_readlane_b32 s5, v254, 14
	s_add_u32 s14, s0, s4
	s_addc_u32 s15, s17, s5
	s_add_i32 s64, s63, 0x2000
	s_mov_b32 m0, s63
	s_add_u32 s4, s14, 0x100000
	global_load_lds_dwordx4 v158, s[14:15]
	s_mov_b32 m0, s64
	s_addc_u32 s5, s15, 0
	s_add_i32 s65, s63, 0x4000
	global_load_lds_dwordx4 v156, s[14:15]
	s_mov_b32 m0, s65
	s_add_i32 s66, s63, 0x6000
	global_load_lds_dwordx4 v158, s[4:5]
	s_mov_b32 m0, s66
	v_mov_b32_e32 v157, v1
	global_load_lds_dwordx4 v156, s[4:5]
	s_cmp_eq_u32 s28, 1
	v_lshl_add_u64 v[8:9], s[12:13], 0, v[0:1]
	v_lshl_add_u64 v[6:7], s[12:13], 0, v[154:155]
	v_lshl_add_u64 v[2:3], s[14:15], 0, v[158:159]
	s_cselect_b64 s[4:5], -1, 0
	s_cmp_lg_u32 s28, 1
	v_lshl_add_u64 v[4:5], s[14:15], 0, v[156:157]
	s_cbranch_scc1 .LBB0_616
	s_barrier
.LBB0_616:
	s_add_u32 s44, s42, 0x4000000
	s_addc_u32 s45, s43, 0
	s_add_u32 s46, s40, 0x4000000
	v_bfe_u32 v17, v16, 4, 2
	s_addc_u32 s47, s41, 0
	v_and_b32_e32 v18, 15, v16
	v_lshlrev_b32_e32 v19, 4, v17
	v_lshlrev_b32_e32 v16, 2, v16
	s_lshl_b32 s21, s21, 5
	v_lshl_or_b32 v182, s28, 6, v18
	v_lshl_or_b32 v18, v18, 6, v19
	s_lshl_b32 s28, s28, 13
	v_and_b32_e32 v16, 32, v16
	s_and_b32 s21, s21, 0x60
	s_add_i32 m0, s63, 0x18000
	v_lshl_add_u64 v[8:9], v[8:9], 0, s[10:11]
	v_bitop3_b32 v19, v18, s28, v16 bitop3:0xde
	s_lshl_b32 s28, s21, 7
	s_waitcnt vmcnt(2)
	s_barrier
	global_load_lds_dwordx4 v[8:9], off
	v_lshl_add_u64 v[6:7], v[6:7], 0, s[10:11]
	s_add_i32 m0, s63, 0x1a000
	s_add_i32 s67, s63, 0x8000
	s_add_i32 s68, s63, 0xa000
	v_bitop3_b32 v183, v18, s28, v16 bitop3:0xde
	global_load_lds_dwordx4 v[6:7], off
	v_lshl_add_u64 v[2:3], v[2:3], 0, s[10:11]
	s_mov_b32 m0, s67
	s_add_u32 s28, s12, 0x40080
	global_load_lds_dwordx4 v[2:3], off
	v_lshl_add_u64 v[2:3], v[4:5], 0, s[10:11]
	s_mov_b32 m0, s68
	s_addc_u32 s29, s13, 0
	global_load_lds_dwordx4 v[2:3], off
	s_add_i32 m0, s63, 0x1c000
	v_lshl_add_u64 v[2:3], s[28:29], 0, v[0:1]
	global_load_lds_dwordx4 v[2:3], off
	v_lshl_add_u64 v[2:3], s[28:29], 0, v[154:155]
	s_add_i32 m0, s63, 0x1e000
	s_cmpk_lt_u32 s20, 0x100
	global_load_lds_dwordx4 v[2:3], off
	v_lshlrev_b32_e32 v2, 16, v10
	v_and_b32_e32 v2, 0xfffe0000, v2
	v_lshl_add_u32 v2, v11, 13, v2
	v_and_b32_e32 v3, 1, v10
	v_lshl_or_b32 v2, v3, 6, v2
	v_lshl_add_u32 v160, v12, 1, v2
	v_lshlrev_b32_e32 v2, 16, v14
	v_and_b32_e32 v2, 0xfffe0000, v2
	s_waitcnt vmcnt(6)
	v_lshl_add_u32 v2, v13, 13, v2
	v_and_b32_e32 v3, 1, v14
	v_lshl_or_b32 v2, v3, 6, v2
	v_readlane_b32 s26, v254, 11
	s_cselect_b64 s[48:49], -1, 0
	s_mov_b32 s69, 0
	v_cmp_eq_u32_e64 s[40:41], 0, v17
	v_lshl_or_b32 v184, v17, 3, s21
	v_add_u32_e32 v184, s21, v184
	v_mov_b32_e32 v161, v1
	v_lshl_add_u32 v162, v15, 1, v2
	v_mov_b32_e32 v163, v1
	v_add_u32_e32 v185, 0, v19
	v_readlane_b32 s20, v255, 59
	s_xor_b32 s21, s26, 24
	s_barrier
	v_readlane_b32 s27, v254, 12
	v_and_b32_e32 v249, 8, v228
	v_mul_u32_u24_e32 v250, 0x7f8, v249
	v_sub_u32_e32 v250, 0, v250
	v_ashrrev_i32_e32 v251, 31, v250
	s_mov_b32 s98, 0x00ff00ff
	s_mov_b32 s99, 0x00ff00ff
	s_mov_b32 s100, 0x4000
	s_mov_b32 s101, 0
	s_branch .LBB0_619

.LBB0_626:
	s_add_i32 s70, 0, 0x10000
	s_add_i32 s72, 0, 0x14000
	v_add_u32_e32 v134, s70, v183
	v_add_u32_e32 v168, s72, v183
	ds_read_b128 v[114:117], v134
	ds_read_b128 v[118:121], v134 offset:1024
	ds_read_b128 v[122:125], v134 offset:2048
	ds_read_b128 v[134:137], v134 offset:3072
	ds_read_b128 v[146:149], v168
	ds_read_b128 v[150:153], v168 offset:1024
	ds_read_b128 v[164:167], v168 offset:2048
	ds_read_b128 v[168:171], v168 offset:3072
	v_lshl_add_u64 v[180:181], s[12:13], 0, v[162:163]
	s_add_i32 m0, s63, 0xc000
	ds_read_b128 v[172:175], v185
	ds_read_b128 v[176:179], v185 offset:1024
	ds_read_b128 v[186:189], v185 offset:2048
	ds_read_b128 v[190:193], v185 offset:3072
	ds_read_b128 v[202:205], v185 offset:4096
	ds_read_b128 v[206:209], v185 offset:5120
	ds_read_b128 v[210:213], v185 offset:6144
	ds_read_b128 v[214:217], v185 offset:7168
	s_add_u32 s14, s12, 0xfff00080
	s_addc_u32 s15, s13, -1
	s_cmp_eq_u32 s53, 60
	s_cselect_b32 s59, s28, s15
	s_cselect_b32 s58, s29, s14
	s_cselect_b32 s15, s33, s51
	s_cselect_b32 s14, s36, s37
	global_load_lds_dwordx4 v[180:181], off
	v_lshl_add_u64 v[180:181], s[12:13], 0, v[160:161]
	s_add_i32 m0, s63, 0xe000
	s_nop 0
	global_load_lds_dwordx4 v[180:181], off
	s_waitcnt vmcnt(8)
	s_waitcnt lgkmcnt(0)
	s_setprio 1
	s_barrier
	v_mfma_f32_16x16x32_bf16 v[142:145], v[114:117], v[172:175], v[142:145]
	v_mfma_f32_16x16x32_bf16 v[138:141], v[122:125], v[172:175], v[138:141]
	v_mfma_f32_16x16x32_bf16 v[110:113], v[114:117], v[186:189], v[110:113]
	v_mfma_f32_16x16x32_bf16 v[106:109], v[122:125], v[186:189], v[106:109]
	v_mfma_f32_16x16x32_bf16 v[94:97], v[114:117], v[202:205], v[94:97]
	v_mfma_f32_16x16x32_bf16 v[90:93], v[122:125], v[202:205], v[90:93]
	v_mfma_f32_16x16x32_bf16 v[78:81], v[114:117], v[210:213], v[78:81]
	v_mfma_f32_16x16x32_bf16 v[74:77], v[122:125], v[210:213], v[74:77]
	v_mfma_f32_16x16x32_bf16 v[142:145], v[118:121], v[176:179], v[142:145]
	v_mfma_f32_16x16x32_bf16 v[138:141], v[134:137], v[176:179], v[138:141]
	v_mfma_f32_16x16x32_bf16 v[110:113], v[118:121], v[190:193], v[110:113]
	v_mfma_f32_16x16x32_bf16 v[106:109], v[134:137], v[190:193], v[106:109]
	v_mfma_f32_16x16x32_bf16 v[94:97], v[118:121], v[206:209], v[94:97]
	v_mfma_f32_16x16x32_bf16 v[90:93], v[134:137], v[206:209], v[90:93]
	v_mfma_f32_16x16x32_bf16 v[78:81], v[118:121], v[214:217], v[78:81]
	v_mfma_f32_16x16x32_bf16 v[74:77], v[134:137], v[214:217], v[74:77]
	v_mfma_f32_16x16x32_bf16 v[130:133], v[146:149], v[172:175], v[130:133]
	v_mfma_f32_16x16x32_bf16 v[126:129], v[164:167], v[172:175], v[126:129]
	v_mfma_f32_16x16x32_bf16 v[102:105], v[146:149], v[186:189], v[102:105]
	v_mfma_f32_16x16x32_bf16 v[98:101], v[164:167], v[186:189], v[98:101]
	v_mfma_f32_16x16x32_bf16 v[86:89], v[146:149], v[202:205], v[86:89]
	v_mfma_f32_16x16x32_bf16 v[82:85], v[164:167], v[202:205], v[82:85]
	v_mfma_f32_16x16x32_bf16 v[70:73], v[146:149], v[210:213], v[70:73]
	v_mfma_f32_16x16x32_bf16 v[66:69], v[164:167], v[210:213], v[66:69]
	v_mfma_f32_16x16x32_bf16 v[130:133], v[150:153], v[176:179], v[130:133]
	v_mfma_f32_16x16x32_bf16 v[126:129], v[168:171], v[176:179], v[126:129]
	v_mfma_f32_16x16x32_bf16 v[102:105], v[150:153], v[190:193], v[102:105]
	v_mfma_f32_16x16x32_bf16 v[98:101], v[168:171], v[190:193], v[98:101]
	v_mfma_f32_16x16x32_bf16 v[86:89], v[150:153], v[206:209], v[86:89]
	v_mfma_f32_16x16x32_bf16 v[82:85], v[168:171], v[206:209], v[82:85]
	v_mfma_f32_16x16x32_bf16 v[70:73], v[150:153], v[214:217], v[70:73]
	v_mfma_f32_16x16x32_bf16 v[66:69], v[168:171], v[214:217], v[66:69]
	s_barrier
	s_setprio 0
	s_add_i32 s70, s70, s62
	v_lshl_add_u64 v[180:181], s[14:15], 0, v[0:1]
	s_mov_b32 m0, s70
	ds_read_b128 v[172:175], v185 offset:16384
	ds_read_b128 v[176:179], v185 offset:17408
	ds_read_b128 v[186:189], v185 offset:18432
	ds_read_b128 v[190:193], v185 offset:19456
	ds_read_b128 v[202:205], v185 offset:20480
	ds_read_b128 v[206:209], v185 offset:21504
	ds_read_b128 v[210:213], v185 offset:22528
	ds_read_b128 v[214:217], v185 offset:23552
	global_load_lds_dwordx4 v[180:181], off
	s_add_i32 m0, s70, 0x2000
	s_add_u32 s70, s14, 0x40000
	v_lshl_add_u64 v[218:219], s[14:15], 0, v[154:155]
	s_addc_u32 s71, s15, 0
	s_add_i32 s72, s72, s62
	global_load_lds_dwordx4 v[218:219], off
	v_lshl_add_u64 v[220:221], s[70:71], 0, v[0:1]
	s_mov_b32 m0, s72
	v_lshl_add_u64 v[222:223], s[58:59], 0, v[156:157]
	global_load_lds_dwordx4 v[220:221], off
	v_lshl_add_u64 v[220:221], s[70:71], 0, v[154:155]
	s_add_i32 m0, s72, 0x2000
	s_nop 0
	global_load_lds_dwordx4 v[220:221], off
	v_lshl_add_u64 v[220:221], s[58:59], 0, v[158:159]
	s_mov_b32 m0, s63
	s_nop 0
	global_load_lds_dwordx4 v[220:221], off
	s_mov_b32 m0, s64
	s_nop 0
	global_load_lds_dwordx4 v[222:223], off
	s_waitcnt vmcnt(8)
	s_waitcnt lgkmcnt(0)
	s_setprio 1
	s_barrier
	v_mfma_f32_16x16x32_bf16 v[62:65], v[114:117], v[172:175], v[62:65]
	v_mfma_f32_16x16x32_bf16 v[58:61], v[122:125], v[172:175], v[58:61]
	v_mfma_f32_16x16x32_bf16 v[46:49], v[114:117], v[186:189], v[46:49]
	v_mfma_f32_16x16x32_bf16 v[42:45], v[122:125], v[186:189], v[42:45]
	v_mfma_f32_16x16x32_bf16 v[30:33], v[114:117], v[202:205], v[30:33]
	v_mfma_f32_16x16x32_bf16 v[26:29], v[122:125], v[202:205], v[26:29]
	v_mfma_f32_16x16x32_bf16 v[14:17], v[114:117], v[210:213], v[14:17]
	v_mfma_f32_16x16x32_bf16 v[10:13], v[122:125], v[210:213], v[10:13]
	v_mfma_f32_16x16x32_bf16 v[62:65], v[118:121], v[176:179], v[62:65]
	v_mfma_f32_16x16x32_bf16 v[58:61], v[134:137], v[176:179], v[58:61]
	v_mfma_f32_16x16x32_bf16 v[46:49], v[118:121], v[190:193], v[46:49]
	v_mfma_f32_16x16x32_bf16 v[42:45], v[134:137], v[190:193], v[42:45]
	v_mfma_f32_16x16x32_bf16 v[30:33], v[118:121], v[206:209], v[30:33]
	v_mfma_f32_16x16x32_bf16 v[26:29], v[134:137], v[206:209], v[26:29]
	v_mfma_f32_16x16x32_bf16 v[14:17], v[118:121], v[214:217], v[14:17]
	v_mfma_f32_16x16x32_bf16 v[10:13], v[134:137], v[214:217], v[10:13]
	v_mfma_f32_16x16x32_bf16 v[54:57], v[146:149], v[172:175], v[54:57]
	v_mfma_f32_16x16x32_bf16 v[50:53], v[164:167], v[172:175], v[50:53]
	v_mfma_f32_16x16x32_bf16 v[38:41], v[146:149], v[186:189], v[38:41]
	v_mfma_f32_16x16x32_bf16 v[34:37], v[164:167], v[186:189], v[34:37]
	v_mfma_f32_16x16x32_bf16 v[22:25], v[146:149], v[202:205], v[22:25]
	v_mfma_f32_16x16x32_bf16 v[18:21], v[164:167], v[202:205], v[18:21]
	v_mfma_f32_16x16x32_bf16 v[6:9], v[146:149], v[210:213], v[6:9]
	v_mfma_f32_16x16x32_bf16 v[2:5], v[164:167], v[210:213], v[2:5]
	v_mfma_f32_16x16x32_bf16 v[54:57], v[150:153], v[176:179], v[54:57]
	v_mfma_f32_16x16x32_bf16 v[50:53], v[168:171], v[176:179], v[50:53]
	v_mfma_f32_16x16x32_bf16 v[38:41], v[150:153], v[190:193], v[38:41]
	v_mfma_f32_16x16x32_bf16 v[34:37], v[168:171], v[190:193], v[34:37]
	v_mfma_f32_16x16x32_bf16 v[22:25], v[150:153], v[206:209], v[22:25]
	v_mfma_f32_16x16x32_bf16 v[18:21], v[168:171], v[206:209], v[18:21]
	v_mfma_f32_16x16x32_bf16 v[6:9], v[150:153], v[214:217], v[6:9]
	v_mfma_f32_16x16x32_bf16 v[2:5], v[168:171], v[214:217], v[2:5]
	s_barrier
	s_setprio 0
	s_add_i32 s70, 0, 0x18000
	s_add_i32 s71, 0, 0x1c000
	v_add_u32_e32 v134, s70, v183
	v_add_u32_e32 v168, s71, v183
	ds_read_b128 v[114:117], v134
	ds_read_b128 v[118:121], v134 offset:1024
	ds_read_b128 v[122:125], v134 offset:2048
	ds_read_b128 v[134:137], v134 offset:3072
	ds_read_b128 v[146:149], v168
	ds_read_b128 v[150:153], v168 offset:1024
	ds_read_b128 v[164:167], v168 offset:2048
	ds_read_b128 v[168:171], v168 offset:3072
	s_add_u32 s58, s58, 0x100000
	s_addc_u32 s59, s59, 0
	s_mov_b32 m0, s65
	v_lshl_add_u64 v[232:233], s[58:59], 0, v[158:159]
	ds_read_b128 v[172:175], v185 offset:32768
	ds_read_b128 v[176:179], v185 offset:33792
	ds_read_b128 v[186:189], v185 offset:34816
	ds_read_b128 v[190:193], v185 offset:35840
	ds_read_b128 v[202:205], v185 offset:36864
	ds_read_b128 v[206:209], v185 offset:37888
	ds_read_b128 v[210:213], v185 offset:38912
	ds_read_b128 v[214:217], v185 offset:39936
	global_load_lds_dwordx4 v[232:233], off
	v_lshl_add_u64 v[232:233], s[58:59], 0, v[156:157]
	s_mov_b32 m0, s66
	s_nop 0
	global_load_lds_dwordx4 v[232:233], off
	s_waitcnt vmcnt(8)
	s_waitcnt lgkmcnt(0)
	s_setprio 1
	s_barrier
	v_mfma_f32_16x16x32_bf16 v[142:145], v[114:117], v[172:175], v[142:145]
	v_mfma_f32_16x16x32_bf16 v[138:141], v[122:125], v[172:175], v[138:141]
	v_mfma_f32_16x16x32_bf16 v[110:113], v[114:117], v[186:189], v[110:113]
	v_mfma_f32_16x16x32_bf16 v[106:109], v[122:125], v[186:189], v[106:109]
	v_mfma_f32_16x16x32_bf16 v[94:97], v[114:117], v[202:205], v[94:97]
	v_mfma_f32_16x16x32_bf16 v[90:93], v[122:125], v[202:205], v[90:93]
	v_mfma_f32_16x16x32_bf16 v[78:81], v[114:117], v[210:213], v[78:81]
	v_mfma_f32_16x16x32_bf16 v[74:77], v[122:125], v[210:213], v[74:77]
	v_mfma_f32_16x16x32_bf16 v[142:145], v[118:121], v[176:179], v[142:145]
	v_mfma_f32_16x16x32_bf16 v[138:141], v[134:137], v[176:179], v[138:141]
	v_mfma_f32_16x16x32_bf16 v[110:113], v[118:121], v[190:193], v[110:113]
	v_mfma_f32_16x16x32_bf16 v[106:109], v[134:137], v[190:193], v[106:109]
	v_mfma_f32_16x16x32_bf16 v[94:97], v[118:121], v[206:209], v[94:97]
	v_mfma_f32_16x16x32_bf16 v[90:93], v[134:137], v[206:209], v[90:93]
	v_mfma_f32_16x16x32_bf16 v[78:81], v[118:121], v[214:217], v[78:81]
	v_mfma_f32_16x16x32_bf16 v[74:77], v[134:137], v[214:217], v[74:77]
	v_mfma_f32_16x16x32_bf16 v[130:133], v[146:149], v[172:175], v[130:133]
	v_mfma_f32_16x16x32_bf16 v[126:129], v[164:167], v[172:175], v[126:129]
	v_mfma_f32_16x16x32_bf16 v[102:105], v[146:149], v[186:189], v[102:105]
	v_mfma_f32_16x16x32_bf16 v[98:101], v[164:167], v[186:189], v[98:101]
	v_mfma_f32_16x16x32_bf16 v[86:89], v[146:149], v[202:205], v[86:89]
	v_mfma_f32_16x16x32_bf16 v[82:85], v[164:167], v[202:205], v[82:85]
	v_mfma_f32_16x16x32_bf16 v[70:73], v[146:149], v[210:213], v[70:73]
	v_mfma_f32_16x16x32_bf16 v[66:69], v[164:167], v[210:213], v[66:69]
	v_mfma_f32_16x16x32_bf16 v[130:133], v[150:153], v[176:179], v[130:133]
	v_mfma_f32_16x16x32_bf16 v[126:129], v[168:171], v[176:179], v[126:129]
	v_mfma_f32_16x16x32_bf16 v[102:105], v[150:153], v[190:193], v[102:105]
	v_mfma_f32_16x16x32_bf16 v[98:101], v[168:171], v[190:193], v[98:101]
	v_mfma_f32_16x16x32_bf16 v[86:89], v[150:153], v[206:209], v[86:89]
	v_mfma_f32_16x16x32_bf16 v[82:85], v[168:171], v[206:209], v[82:85]
	v_mfma_f32_16x16x32_bf16 v[70:73], v[150:153], v[214:217], v[70:73]
	v_mfma_f32_16x16x32_bf16 v[66:69], v[168:171], v[214:217], v[66:69]
	s_barrier
	s_setprio 0
	s_add_i32 s58, s70, s62
	v_lshl_add_u64 v[180:181], v[180:181], 0, s[10:11]
	s_mov_b32 m0, s58
	ds_read_b128 v[172:175], v185 offset:49152
	ds_read_b128 v[176:179], v185 offset:50176
	ds_read_b128 v[186:189], v185 offset:51200
	ds_read_b128 v[190:193], v185 offset:52224
	ds_read_b128 v[202:205], v185 offset:53248
	ds_read_b128 v[206:209], v185 offset:54272
	ds_read_b128 v[210:213], v185 offset:55296
	ds_read_b128 v[214:217], v185 offset:56320
	s_add_i32 s53, s53, 2
	s_add_u32 s37, s37, 0x100
	s_addc_u32 s51, s51, 0
	s_add_u32 s12, s12, 0x100
	s_addc_u32 s13, s13, 0
	global_load_lds_dwordx4 v[180:181], off
	s_add_i32 m0, s58, 0x2000
	s_add_u32 s14, s14, 0x40080
	v_lshl_add_u64 v[180:181], v[218:219], 0, s[10:11]
	s_addc_u32 s15, s15, 0
	s_add_i32 s58, s71, s62
	global_load_lds_dwordx4 v[180:181], off
	v_lshl_add_u64 v[180:181], s[14:15], 0, v[0:1]
	s_mov_b32 m0, s58
	s_nop 0
	global_load_lds_dwordx4 v[180:181], off
	v_lshl_add_u64 v[180:181], s[14:15], 0, v[154:155]
	s_add_i32 m0, s58, 0x2000
	s_nop 0
	global_load_lds_dwordx4 v[180:181], off
	v_lshl_add_u64 v[180:181], v[220:221], 0, s[10:11]
	s_mov_b32 m0, s67
	s_nop 0
	global_load_lds_dwordx4 v[180:181], off
	v_lshl_add_u64 v[180:181], v[222:223], 0, s[10:11]
	s_mov_b32 m0, s68
	s_nop 0
	global_load_lds_dwordx4 v[180:181], off
	s_waitcnt vmcnt(8)
	s_waitcnt lgkmcnt(0)
	s_setprio 1
	s_barrier
	v_mfma_f32_16x16x32_bf16 v[62:65], v[114:117], v[172:175], v[62:65]
	v_mfma_f32_16x16x32_bf16 v[58:61], v[122:125], v[172:175], v[58:61]
	v_mfma_f32_16x16x32_bf16 v[46:49], v[114:117], v[186:189], v[46:49]
	v_mfma_f32_16x16x32_bf16 v[42:45], v[122:125], v[186:189], v[42:45]
	v_mfma_f32_16x16x32_bf16 v[30:33], v[114:117], v[202:205], v[30:33]
	v_mfma_f32_16x16x32_bf16 v[26:29], v[122:125], v[202:205], v[26:29]
	v_mfma_f32_16x16x32_bf16 v[14:17], v[114:117], v[210:213], v[14:17]
	v_mfma_f32_16x16x32_bf16 v[10:13], v[122:125], v[210:213], v[10:13]
	v_mfma_f32_16x16x32_bf16 v[62:65], v[118:121], v[176:179], v[62:65]
	v_mfma_f32_16x16x32_bf16 v[58:61], v[134:137], v[176:179], v[58:61]
	v_mfma_f32_16x16x32_bf16 v[46:49], v[118:121], v[190:193], v[46:49]
	v_mfma_f32_16x16x32_bf16 v[42:45], v[134:137], v[190:193], v[42:45]
	v_mfma_f32_16x16x32_bf16 v[30:33], v[118:121], v[206:209], v[30:33]
	v_mfma_f32_16x16x32_bf16 v[26:29], v[134:137], v[206:209], v[26:29]
	v_mfma_f32_16x16x32_bf16 v[14:17], v[118:121], v[214:217], v[14:17]
	v_mfma_f32_16x16x32_bf16 v[10:13], v[134:137], v[214:217], v[10:13]
	v_mfma_f32_16x16x32_bf16 v[54:57], v[146:149], v[172:175], v[54:57]
	v_mfma_f32_16x16x32_bf16 v[50:53], v[164:167], v[172:175], v[50:53]
	v_mfma_f32_16x16x32_bf16 v[38:41], v[146:149], v[186:189], v[38:41]
	v_mfma_f32_16x16x32_bf16 v[34:37], v[164:167], v[186:189], v[34:37]
	v_mfma_f32_16x16x32_bf16 v[22:25], v[146:149], v[202:205], v[22:25]
	v_mfma_f32_16x16x32_bf16 v[18:21], v[164:167], v[202:205], v[18:21]
	v_mfma_f32_16x16x32_bf16 v[6:9], v[146:149], v[210:213], v[6:9]
	v_mfma_f32_16x16x32_bf16 v[2:5], v[164:167], v[210:213], v[2:5]
	v_mfma_f32_16x16x32_bf16 v[54:57], v[150:153], v[176:179], v[54:57]
	v_mfma_f32_16x16x32_bf16 v[50:53], v[168:171], v[176:179], v[50:53]
	v_mfma_f32_16x16x32_bf16 v[38:41], v[150:153], v[190:193], v[38:41]
	v_mfma_f32_16x16x32_bf16 v[34:37], v[168:171], v[190:193], v[34:37]
	v_mfma_f32_16x16x32_bf16 v[22:25], v[150:153], v[206:209], v[22:25]
	v_mfma_f32_16x16x32_bf16 v[18:21], v[168:171], v[206:209], v[18:21]
	v_mfma_f32_16x16x32_bf16 v[6:9], v[150:153], v[214:217], v[6:9]
	v_mfma_f32_16x16x32_bf16 v[2:5], v[168:171], v[214:217], v[2:5]
	s_barrier
	s_setprio 0
	s_cmp_gt_u32 s53, 61
	s_cbranch_scc0 .LBB0_626
	s_and_b64 vcc, exec, s[48:49]
	s_cbranch_vccz .LBB0_629
	s_barrier
.LBB0_629:
	v_lshl_or_b32 v164, s20, 8, v184
	v_lshl_add_u32 v168, s21, 8, v182
	v_ashrrev_i32_e32 v165, 31, v164
	v_lshlrev_b64 v[202:203], 1, v[164:165]
	v_ashrrev_i32_e32 v169, 31, v168
	v_lshl_add_u64 v[166:167], s[44:45], 0, v[202:203]
	v_lshlrev_b64 v[204:205], 11, v[168:169]
	v_lshl_add_u64 v[114:115], v[166:167], 0, v[204:205]
	flat_load_dwordx4 v[186:189], v[114:115]
	flat_load_dwordx4 v[190:193], v[114:115] offset:64
	v_or_b32_e32 v178, 16, v168
	v_ashrrev_i32_e32 v179, 31, v178
	v_or_b32_e32 v174, 32, v168
	v_lshlrev_b64 v[180:181], 11, v[178:179]
	v_ashrrev_i32_e32 v175, 31, v174
	v_or_b32_e32 v170, 48, v168
	v_lshl_add_u64 v[114:115], v[166:167], 0, v[180:181]
	v_lshlrev_b64 v[176:177], 11, v[174:175]
	v_ashrrev_i32_e32 v171, 31, v170
	flat_load_dwordx4 v[150:153], v[114:115]
	flat_load_dwordx4 v[146:149], v[114:115] offset:64
	v_lshl_add_u64 v[114:115], v[166:167], 0, v[176:177]
	v_lshlrev_b64 v[172:173], 11, v[170:171]
	flat_load_dwordx4 v[134:137], v[114:115]
	flat_load_dwordx4 v[122:125], v[114:115] offset:64
	v_lshl_add_u64 v[114:115], v[166:167], 0, v[172:173]
	flat_load_dwordx4 v[118:121], v[114:115]
	s_nop 0
	flat_load_dwordx4 v[114:117], v[114:115] offset:64
	v_lshl_add_u64 v[204:205], s[46:47], 0, v[204:205]
	v_lshl_add_u64 v[202:203], v[204:205], 0, v[202:203]
	s_waitcnt vmcnt(0) lgkmcnt(0)
	v_lshlrev_b32_e32 v206, 16, v186
	v_and_b32_e32 v207, 0xffff0000, v186
	v_lshlrev_b32_e32 v186, 16, v187
	v_and_b32_e32 v187, 0xffff0000, v187
	v_lshlrev_b32_e32 v208, 16, v188
	v_and_b32_e32 v209, 0xffff0000, v188
	v_lshlrev_b32_e32 v188, 16, v189
	v_and_b32_e32 v189, 0xffff0000, v189
	v_pk_add_f32 v[144:145], v[144:145], v[186:187]
	v_pk_add_f32 v[142:143], v[142:143], v[206:207]
	v_pk_add_f32 v[186:187], v[140:141], v[188:189]
	v_pk_add_f32 v[188:189], v[138:139], v[208:209]
	v_cvt_pk_bf16_f32 v138, v142, v143
	v_cvt_pk_bf16_f32 v139, v144, v145
	s_nop 0
	v_cvt_pk_bf16_f32 v140, v188, v189
	v_cvt_pk_bf16_f32 v141, v186, v187
	v_mov_b32_e32 v244, v138
	v_mov_b32_e32 v245, v139
	v_mov_b32_e32 v246, v140
	v_mov_b32_e32 v247, v141
	s_nop 1
	v_mul_f32_e32 v138, v143, v143
	v_mul_f32_e32 v139, v145, v145
	v_fmac_f32_e32 v138, v142, v142
	v_fmac_f32_e32 v139, v144, v144
	v_add_f32_e32 v138, v138, v139
	v_mul_f32_e32 v139, v189, v189
	v_fmac_f32_e32 v139, v188, v188
	v_add_f32_e32 v138, v139, v138
	v_mul_f32_e32 v139, v187, v187
	v_fmac_f32_e32 v139, v186, v186
	v_add_f32_e32 v186, v139, v138
	v_lshlrev_b32_e32 v138, 16, v190
	v_and_b32_e32 v139, 0xffff0000, v190
	v_lshlrev_b32_e32 v140, 16, v191
	v_and_b32_e32 v141, 0xffff0000, v191
	v_lshlrev_b32_e32 v142, 16, v192
	v_and_b32_e32 v143, 0xffff0000, v192
	v_lshlrev_b32_e32 v144, 16, v193
	v_and_b32_e32 v145, 0xffff0000, v193
	v_pk_add_f32 v[132:133], v[132:133], v[140:141]
	v_pk_add_f32 v[130:131], v[130:131], v[138:139]
	v_pk_add_f32 v[140:141], v[126:127], v[142:143]
	v_cvt_pk_bf16_f32 v126, v130, v131
	v_cvt_pk_bf16_f32 v127, v132, v133
	v_pk_add_f32 v[138:139], v[128:129], v[144:145]
	v_cvt_pk_bf16_f32 v128, v140, v141
	s_nop 0
	v_cvt_pk_bf16_f32 v129, v138, v139
	v_mov_b32_dpp v252, v244 row_ror:8 row_mask:0xf bank_mask:0xf
	v_mov_b32_dpp v226, v126 row_ror:8 row_mask:0xf bank_mask:0xf
	v_cndmask_b32_e64 v126, v126, v252, s[98:99]
	v_cndmask_b32_e64 v244, v226, v244, s[98:99]
	v_mov_b32_dpp v252, v245 row_ror:8 row_mask:0xf bank_mask:0xf
	v_mov_b32_dpp v226, v127 row_ror:8 row_mask:0xf bank_mask:0xf
	v_cndmask_b32_e64 v127, v127, v252, s[98:99]
	v_cndmask_b32_e64 v245, v226, v245, s[98:99]
	v_mov_b32_dpp v252, v246 row_ror:8 row_mask:0xf bank_mask:0xf
	v_mov_b32_dpp v226, v128 row_ror:8 row_mask:0xf bank_mask:0xf
	v_cndmask_b32_e64 v128, v128, v252, s[98:99]
	v_cndmask_b32_e64 v246, v226, v246, s[98:99]
	v_mov_b32_dpp v252, v247 row_ror:8 row_mask:0xf bank_mask:0xf
	v_mov_b32_dpp v226, v129 row_ror:8 row_mask:0xf bank_mask:0xf
	v_cndmask_b32_e64 v129, v129, v252, s[98:99]
	v_cndmask_b32_e64 v247, v226, v247, s[98:99]
	v_lshl_add_u64 v[240:241], v[202:203], 0, v[250:251]
	v_lshl_add_u64 v[242:243], v[240:241], 0, s[100:101]
	flat_store_dwordx4 v[240:241], v[244:247]
	flat_store_dwordx4 v[242:243], v[126:129]
	s_nop 1
	v_mul_f32_e32 v126, v131, v131
	v_mul_f32_e32 v127, v133, v133
	v_fmac_f32_e32 v126, v130, v130
	v_fmac_f32_e32 v127, v132, v132
	v_add_f32_e32 v126, v126, v127
	v_mul_f32_e32 v127, v141, v141
	v_fmac_f32_e32 v127, v140, v140
	v_add_f32_e32 v126, v127, v126
	v_mul_f32_e32 v127, v139, v139
	v_fmac_f32_e32 v127, v138, v138
	v_add_f32_e32 v126, v127, v126
	v_and_b32_e32 v128, 64, v228
	v_add_f32_e32 v127, v186, v126
	v_xor_b32_e32 v126, 16, v228
	v_add_u32_e32 v129, 64, v128
	v_cmp_lt_i32_e32 vcc, v126, v129
	s_nop 1
	v_cndmask_b32_e32 v126, v228, v126, vcc
	v_lshlrev_b32_e32 v126, 2, v126
	ds_bpermute_b32 v128, v126, v127
	s_waitcnt lgkmcnt(0)
	v_add_f32_e32 v128, v127, v128
	v_xor_b32_e32 v127, 32, v228
	v_cmp_lt_i32_e32 vcc, v127, v129
	s_nop 1
	v_cndmask_b32_e32 v127, v228, v127, vcc
	v_lshlrev_b32_e32 v127, 2, v127
	ds_bpermute_b32 v129, v127, v128
	s_and_saveexec_b64 s[12:13], s[40:41]
	s_cbranch_execz .LBB0_631
	v_lshl_add_u64 v[130:131], v[168:169], 2, s[18:19]
	s_waitcnt lgkmcnt(0)
	v_add_f32_e32 v128, v128, v129
	flat_atomic_add_f32 v[130:131], v128
.LBB0_631:
	s_or_b64 exec, exec, s[12:13]
	v_lshlrev_b32_e32 v128, 16, v150
	s_waitcnt lgkmcnt(0)
	v_and_b32_e32 v129, 0xffff0000, v150
	v_lshlrev_b32_e32 v130, 16, v151
	v_and_b32_e32 v131, 0xffff0000, v151
	v_lshlrev_b32_e32 v132, 16, v152
	v_and_b32_e32 v133, 0xffff0000, v152
	v_pk_add_f32 v[110:111], v[110:111], v[128:129]
	v_pk_add_f32 v[112:113], v[112:113], v[130:131]
	v_pk_add_f32 v[130:131], v[106:107], v[132:133]
	v_cvt_pk_bf16_f32 v106, v110, v111
	v_mul_f32_e32 v111, v111, v111
	v_fmac_f32_e32 v111, v110, v110
	v_mul_f32_e32 v110, v113, v113
	v_fmac_f32_e32 v110, v112, v112
	v_lshlrev_b32_e32 v138, 16, v153
	v_and_b32_e32 v139, 0xffff0000, v153
	v_add_f32_e32 v110, v111, v110
	v_mul_f32_e32 v111, v131, v131
	v_pk_add_f32 v[128:129], v[108:109], v[138:139]
	v_fmac_f32_e32 v111, v130, v130
	v_add_f32_e32 v110, v111, v110
	v_mul_f32_e32 v111, v129, v129
	v_fmac_f32_e32 v111, v128, v128
	v_cvt_pk_bf16_f32 v107, v112, v113
	v_add_f32_e32 v132, v111, v110
	v_lshlrev_b32_e32 v110, 16, v146
	v_and_b32_e32 v111, 0xffff0000, v146
	v_lshlrev_b32_e32 v112, 16, v147
	v_and_b32_e32 v113, 0xffff0000, v147
	v_cvt_pk_bf16_f32 v108, v130, v131
	v_cvt_pk_bf16_f32 v109, v128, v129
	v_lshlrev_b32_e32 v128, 16, v148
	v_and_b32_e32 v129, 0xffff0000, v148
	v_pk_add_f32 v[104:105], v[104:105], v[112:113]
	v_pk_add_f32 v[102:103], v[102:103], v[110:111]
	v_pk_add_f32 v[112:113], v[98:99], v[128:129]
	v_mul_f32_e32 v98, v103, v103
	v_mul_f32_e32 v99, v105, v105
	v_fmac_f32_e32 v98, v102, v102
	v_fmac_f32_e32 v99, v104, v104
	v_lshlrev_b32_e32 v130, 16, v149
	v_and_b32_e32 v131, 0xffff0000, v149
	v_add_f32_e32 v98, v98, v99
	v_mul_f32_e32 v99, v113, v113
	v_pk_add_f32 v[110:111], v[100:101], v[130:131]
	v_fmac_f32_e32 v99, v112, v112
	v_add_f32_e32 v98, v99, v98
	v_mul_f32_e32 v99, v111, v111
	v_fmac_f32_e32 v99, v110, v110
	v_add_f32_e32 v98, v99, v98
	v_add_f32_e32 v101, v132, v98
	ds_bpermute_b32 v130, v126, v101
	v_lshl_add_u64 v[98:99], s[46:47], 0, v[180:181]
	v_lshl_add_u64 v[128:129], v[164:165], 1, v[98:99]
	v_mov_b32_e32 v244, v106
	v_mov_b32_e32 v245, v107
	v_mov_b32_e32 v246, v108
	v_mov_b32_e32 v247, v109
	v_cvt_pk_bf16_f32 v100, v102, v103
	s_waitcnt lgkmcnt(0)
	v_add_f32_e32 v98, v101, v130
	ds_bpermute_b32 v99, v127, v98
	v_cvt_pk_bf16_f32 v101, v104, v105
	v_cvt_pk_bf16_f32 v102, v112, v113
	v_cvt_pk_bf16_f32 v103, v110, v111
	v_mov_b32_dpp v252, v244 row_ror:8 row_mask:0xf bank_mask:0xf
	v_mov_b32_dpp v226, v100 row_ror:8 row_mask:0xf bank_mask:0xf
	v_cndmask_b32_e64 v100, v100, v252, s[98:99]
	v_cndmask_b32_e64 v244, v226, v244, s[98:99]
	v_mov_b32_dpp v252, v245 row_ror:8 row_mask:0xf bank_mask:0xf
	v_mov_b32_dpp v226, v101 row_ror:8 row_mask:0xf bank_mask:0xf
	v_cndmask_b32_e64 v101, v101, v252, s[98:99]
	v_cndmask_b32_e64 v245, v226, v245, s[98:99]
	v_mov_b32_dpp v252, v246 row_ror:8 row_mask:0xf bank_mask:0xf
	v_mov_b32_dpp v226, v102 row_ror:8 row_mask:0xf bank_mask:0xf
	v_cndmask_b32_e64 v102, v102, v252, s[98:99]
	v_cndmask_b32_e64 v246, v226, v246, s[98:99]
	v_mov_b32_dpp v252, v247 row_ror:8 row_mask:0xf bank_mask:0xf
	v_mov_b32_dpp v226, v103 row_ror:8 row_mask:0xf bank_mask:0xf
	v_cndmask_b32_e64 v103, v103, v252, s[98:99]
	v_cndmask_b32_e64 v247, v226, v247, s[98:99]
	v_lshl_add_u64 v[240:241], v[128:129], 0, v[250:251]
	v_lshl_add_u64 v[242:243], v[240:241], 0, s[100:101]
	flat_store_dwordx4 v[240:241], v[244:247]
	flat_store_dwordx4 v[242:243], v[100:103]
	s_and_saveexec_b64 s[12:13], s[40:41]
	s_cbranch_execz .LBB0_633
	v_lshl_add_u64 v[100:101], v[178:179], 2, s[18:19]
	s_waitcnt lgkmcnt(0)
	v_add_f32_e32 v98, v98, v99
	flat_atomic_add_f32 v[100:101], v98
.LBB0_633:
	s_or_b64 exec, exec, s[12:13]
	v_lshlrev_b32_e32 v98, 16, v134
	s_waitcnt lgkmcnt(0)
	v_and_b32_e32 v99, 0xffff0000, v134
	v_lshlrev_b32_e32 v100, 16, v135
	v_and_b32_e32 v101, 0xffff0000, v135
	v_lshlrev_b32_e32 v102, 16, v136
	v_and_b32_e32 v103, 0xffff0000, v136
	v_pk_add_f32 v[94:95], v[94:95], v[98:99]
	v_pk_add_f32 v[96:97], v[96:97], v[100:101]
	v_pk_add_f32 v[100:101], v[90:91], v[102:103]
	v_cvt_pk_bf16_f32 v90, v94, v95
	v_mul_f32_e32 v95, v95, v95
	v_fmac_f32_e32 v95, v94, v94
	v_mul_f32_e32 v94, v97, v97
	v_fmac_f32_e32 v94, v96, v96
	v_lshlrev_b32_e32 v104, 16, v137
	v_and_b32_e32 v105, 0xffff0000, v137
	v_add_f32_e32 v94, v95, v94
	v_mul_f32_e32 v95, v101, v101
	v_pk_add_f32 v[98:99], v[92:93], v[104:105]
	v_fmac_f32_e32 v95, v100, v100
	v_add_f32_e32 v94, v95, v94
	v_mul_f32_e32 v95, v99, v99
	v_fmac_f32_e32 v95, v98, v98
	v_cvt_pk_bf16_f32 v91, v96, v97
	v_add_f32_e32 v102, v95, v94
	v_lshlrev_b32_e32 v94, 16, v122
	v_and_b32_e32 v95, 0xffff0000, v122
	v_lshlrev_b32_e32 v96, 16, v123
	v_and_b32_e32 v97, 0xffff0000, v123
	v_cvt_pk_bf16_f32 v92, v100, v101
	v_cvt_pk_bf16_f32 v93, v98, v99
	v_lshlrev_b32_e32 v98, 16, v124
	v_and_b32_e32 v99, 0xffff0000, v124
	v_pk_add_f32 v[88:89], v[88:89], v[96:97]
	v_pk_add_f32 v[86:87], v[86:87], v[94:95]
	v_pk_add_f32 v[96:97], v[82:83], v[98:99]
	v_mul_f32_e32 v82, v87, v87
	v_mul_f32_e32 v83, v89, v89
	v_fmac_f32_e32 v82, v86, v86
	v_fmac_f32_e32 v83, v88, v88
	v_lshlrev_b32_e32 v100, 16, v125
	v_and_b32_e32 v101, 0xffff0000, v125
	v_add_f32_e32 v82, v82, v83
	v_mul_f32_e32 v83, v97, v97
	v_pk_add_f32 v[94:95], v[84:85], v[100:101]
	v_fmac_f32_e32 v83, v96, v96
	v_add_f32_e32 v82, v83, v82
	v_mul_f32_e32 v83, v95, v95
	v_fmac_f32_e32 v83, v94, v94
	v_add_f32_e32 v82, v83, v82
	v_add_f32_e32 v85, v102, v82
	ds_bpermute_b32 v100, v126, v85
	v_lshl_add_u64 v[82:83], s[46:47], 0, v[176:177]
	v_lshl_add_u64 v[98:99], v[164:165], 1, v[82:83]
	v_mov_b32_e32 v244, v90
	v_mov_b32_e32 v245, v91
	v_mov_b32_e32 v246, v92
	v_mov_b32_e32 v247, v93
	v_cvt_pk_bf16_f32 v84, v86, v87
	s_waitcnt lgkmcnt(0)
	v_add_f32_e32 v82, v85, v100
	ds_bpermute_b32 v83, v127, v82
	v_cvt_pk_bf16_f32 v85, v88, v89
	v_cvt_pk_bf16_f32 v86, v96, v97
	v_cvt_pk_bf16_f32 v87, v94, v95
	v_mov_b32_dpp v252, v244 row_ror:8 row_mask:0xf bank_mask:0xf
	v_mov_b32_dpp v226, v84 row_ror:8 row_mask:0xf bank_mask:0xf
	v_cndmask_b32_e64 v84, v84, v252, s[98:99]
	v_cndmask_b32_e64 v244, v226, v244, s[98:99]
	v_mov_b32_dpp v252, v245 row_ror:8 row_mask:0xf bank_mask:0xf
	v_mov_b32_dpp v226, v85 row_ror:8 row_mask:0xf bank_mask:0xf
	v_cndmask_b32_e64 v85, v85, v252, s[98:99]
	v_cndmask_b32_e64 v245, v226, v245, s[98:99]
	v_mov_b32_dpp v252, v246 row_ror:8 row_mask:0xf bank_mask:0xf
	v_mov_b32_dpp v226, v86 row_ror:8 row_mask:0xf bank_mask:0xf
	v_cndmask_b32_e64 v86, v86, v252, s[98:99]
	v_cndmask_b32_e64 v246, v226, v246, s[98:99]
	v_mov_b32_dpp v252, v247 row_ror:8 row_mask:0xf bank_mask:0xf
	v_mov_b32_dpp v226, v87 row_ror:8 row_mask:0xf bank_mask:0xf
	v_cndmask_b32_e64 v87, v87, v252, s[98:99]
	v_cndmask_b32_e64 v247, v226, v247, s[98:99]
	v_lshl_add_u64 v[240:241], v[98:99], 0, v[250:251]
	v_lshl_add_u64 v[242:243], v[240:241], 0, s[100:101]
	flat_store_dwordx4 v[240:241], v[244:247]
	flat_store_dwordx4 v[242:243], v[84:87]
	s_and_saveexec_b64 s[12:13], s[40:41]
	s_cbranch_execz .LBB0_635
	v_lshl_add_u64 v[84:85], v[174:175], 2, s[18:19]
	s_waitcnt lgkmcnt(0)
	v_add_f32_e32 v82, v82, v83
	flat_atomic_add_f32 v[84:85], v82
.LBB0_635:
	s_or_b64 exec, exec, s[12:13]
	v_lshlrev_b32_e32 v82, 16, v118
	s_waitcnt lgkmcnt(0)
	v_and_b32_e32 v83, 0xffff0000, v118
	v_lshlrev_b32_e32 v84, 16, v119
	v_and_b32_e32 v85, 0xffff0000, v119
	v_lshlrev_b32_e32 v86, 16, v120
	v_and_b32_e32 v87, 0xffff0000, v120
	v_pk_add_f32 v[78:79], v[78:79], v[82:83]
	v_pk_add_f32 v[80:81], v[80:81], v[84:85]
	v_pk_add_f32 v[84:85], v[74:75], v[86:87]
	v_cvt_pk_bf16_f32 v74, v78, v79
	v_mul_f32_e32 v79, v79, v79
	v_fmac_f32_e32 v79, v78, v78
	v_mul_f32_e32 v78, v81, v81
	v_fmac_f32_e32 v78, v80, v80
	v_lshlrev_b32_e32 v88, 16, v121
	v_and_b32_e32 v89, 0xffff0000, v121
	v_add_f32_e32 v78, v79, v78
	v_mul_f32_e32 v79, v85, v85
	v_pk_add_f32 v[82:83], v[76:77], v[88:89]
	v_fmac_f32_e32 v79, v84, v84
	v_add_f32_e32 v78, v79, v78
	v_mul_f32_e32 v79, v83, v83
	v_fmac_f32_e32 v79, v82, v82
	v_cvt_pk_bf16_f32 v75, v80, v81
	v_add_f32_e32 v86, v79, v78
	v_lshlrev_b32_e32 v78, 16, v114
	v_and_b32_e32 v79, 0xffff0000, v114
	v_lshlrev_b32_e32 v80, 16, v115
	v_and_b32_e32 v81, 0xffff0000, v115
	v_cvt_pk_bf16_f32 v76, v84, v85
	v_cvt_pk_bf16_f32 v77, v82, v83
	v_lshlrev_b32_e32 v82, 16, v116
	v_and_b32_e32 v83, 0xffff0000, v116
	v_pk_add_f32 v[72:73], v[72:73], v[80:81]
	v_pk_add_f32 v[70:71], v[70:71], v[78:79]
	v_pk_add_f32 v[80:81], v[66:67], v[82:83]
	v_mul_f32_e32 v66, v71, v71
	v_mul_f32_e32 v67, v73, v73
	v_fmac_f32_e32 v66, v70, v70
	v_fmac_f32_e32 v67, v72, v72
	v_lshlrev_b32_e32 v84, 16, v117
	v_and_b32_e32 v85, 0xffff0000, v117
	v_add_f32_e32 v66, v66, v67
	v_mul_f32_e32 v67, v81, v81
	v_pk_add_f32 v[78:79], v[68:69], v[84:85]
	v_fmac_f32_e32 v67, v80, v80
	v_add_f32_e32 v66, v67, v66
	v_mul_f32_e32 v67, v79, v79
	v_fmac_f32_e32 v67, v78, v78
	v_add_f32_e32 v66, v67, v66
	v_add_f32_e32 v69, v86, v66
	ds_bpermute_b32 v84, v126, v69
	v_lshl_add_u64 v[66:67], s[46:47], 0, v[172:173]
	v_lshl_add_u64 v[82:83], v[164:165], 1, v[66:67]
	v_mov_b32_e32 v244, v74
	v_mov_b32_e32 v245, v75
	v_mov_b32_e32 v246, v76
	v_mov_b32_e32 v247, v77
	v_cvt_pk_bf16_f32 v68, v70, v71
	s_waitcnt lgkmcnt(0)
	v_add_f32_e32 v66, v69, v84
	ds_bpermute_b32 v67, v127, v66
	v_cvt_pk_bf16_f32 v69, v72, v73
	v_cvt_pk_bf16_f32 v70, v80, v81
	v_cvt_pk_bf16_f32 v71, v78, v79
	v_mov_b32_dpp v252, v244 row_ror:8 row_mask:0xf bank_mask:0xf
	v_mov_b32_dpp v226, v68 row_ror:8 row_mask:0xf bank_mask:0xf
	v_cndmask_b32_e64 v68, v68, v252, s[98:99]
	v_cndmask_b32_e64 v244, v226, v244, s[98:99]
	v_mov_b32_dpp v252, v245 row_ror:8 row_mask:0xf bank_mask:0xf
	v_mov_b32_dpp v226, v69 row_ror:8 row_mask:0xf bank_mask:0xf
	v_cndmask_b32_e64 v69, v69, v252, s[98:99]
	v_cndmask_b32_e64 v245, v226, v245, s[98:99]
	v_mov_b32_dpp v252, v246 row_ror:8 row_mask:0xf bank_mask:0xf
	v_mov_b32_dpp v226, v70 row_ror:8 row_mask:0xf bank_mask:0xf
	v_cndmask_b32_e64 v70, v70, v252, s[98:99]
	v_cndmask_b32_e64 v246, v226, v246, s[98:99]
	v_mov_b32_dpp v252, v247 row_ror:8 row_mask:0xf bank_mask:0xf
	v_mov_b32_dpp v226, v71 row_ror:8 row_mask:0xf bank_mask:0xf
	v_cndmask_b32_e64 v71, v71, v252, s[98:99]
	v_cndmask_b32_e64 v247, v226, v247, s[98:99]
	v_lshl_add_u64 v[240:241], v[82:83], 0, v[250:251]
	v_lshl_add_u64 v[242:243], v[240:241], 0, s[100:101]
	flat_store_dwordx4 v[240:241], v[244:247]
	flat_store_dwordx4 v[242:243], v[68:71]
	s_and_saveexec_b64 s[12:13], s[40:41]
	s_cbranch_execz .LBB0_637
	v_lshl_add_u64 v[68:69], v[170:171], 2, s[18:19]
	s_waitcnt lgkmcnt(0)
	v_add_f32_e32 v66, v66, v67
	flat_atomic_add_f32 v[68:69], v66
.LBB0_637:
	s_or_b64 exec, exec, s[12:13]
	v_add_u32_e32 v106, 0x80, v168
	v_ashrrev_i32_e32 v107, 31, v106
	v_lshlrev_b64 v[112:113], 11, v[106:107]
	s_waitcnt lgkmcnt(0)
	v_lshl_add_u64 v[66:67], v[166:167], 0, v[112:113]
	flat_load_dwordx4 v[108:111], v[66:67]
	flat_load_dwordx4 v[90:93], v[66:67] offset:64
	v_add_u32_e32 v102, 0x90, v168
	v_ashrrev_i32_e32 v103, 31, v102
	v_add_u32_e32 v98, 0xa0, v168
	v_lshlrev_b64 v[104:105], 11, v[102:103]
	v_ashrrev_i32_e32 v99, 31, v98
	v_add_u32_e32 v94, 0xb0, v168
	v_lshl_add_u64 v[66:67], v[166:167], 0, v[104:105]
	v_lshlrev_b64 v[100:101], 11, v[98:99]
	v_ashrrev_i32_e32 v95, 31, v94
	flat_load_dwordx4 v[86:89], v[66:67]
	flat_load_dwordx4 v[82:85], v[66:67] offset:64
	v_lshl_add_u64 v[66:67], v[166:167], 0, v[100:101]
	v_lshlrev_b64 v[96:97], 11, v[94:95]
	flat_load_dwordx4 v[78:81], v[66:67]
	flat_load_dwordx4 v[74:77], v[66:67] offset:64
	v_lshl_add_u64 v[66:67], v[166:167], 0, v[96:97]
	flat_load_dwordx4 v[70:73], v[66:67]
	s_nop 0
	flat_load_dwordx4 v[66:69], v[66:67] offset:64
	v_lshl_add_u64 v[112:113], s[46:47], 0, v[112:113]
	v_lshl_add_u64 v[112:113], v[164:165], 1, v[112:113]
	s_waitcnt vmcnt(0) lgkmcnt(0)
	v_lshlrev_b32_e32 v114, 16, v108
	v_and_b32_e32 v115, 0xffff0000, v108
	v_lshlrev_b32_e32 v108, 16, v109
	v_and_b32_e32 v109, 0xffff0000, v109
	v_lshlrev_b32_e32 v116, 16, v110
	v_and_b32_e32 v117, 0xffff0000, v110
	v_lshlrev_b32_e32 v110, 16, v111
	v_and_b32_e32 v111, 0xffff0000, v111
	v_pk_add_f32 v[64:65], v[64:65], v[108:109]
	v_pk_add_f32 v[62:63], v[62:63], v[114:115]
	v_pk_add_f32 v[108:109], v[60:61], v[110:111]
	v_pk_add_f32 v[110:111], v[58:59], v[116:117]
	v_cvt_pk_bf16_f32 v58, v62, v63
	v_cvt_pk_bf16_f32 v59, v64, v65
	s_nop 0
	v_cvt_pk_bf16_f32 v60, v110, v111
	v_cvt_pk_bf16_f32 v61, v108, v109
	v_mov_b32_e32 v244, v58
	v_mov_b32_e32 v245, v59
	v_mov_b32_e32 v246, v60
	v_mov_b32_e32 v247, v61
	s_nop 1
	v_mul_f32_e32 v58, v63, v63
	v_mul_f32_e32 v59, v65, v65
	v_fmac_f32_e32 v58, v62, v62
	v_fmac_f32_e32 v59, v64, v64
	v_add_f32_e32 v58, v58, v59
	v_mul_f32_e32 v59, v111, v111
	v_fmac_f32_e32 v59, v110, v110
	v_add_f32_e32 v58, v59, v58
	v_mul_f32_e32 v59, v109, v109
	v_fmac_f32_e32 v59, v108, v108
	v_add_f32_e32 v108, v59, v58
	v_lshlrev_b32_e32 v58, 16, v90
	v_and_b32_e32 v59, 0xffff0000, v90
	v_lshlrev_b32_e32 v60, 16, v91
	v_and_b32_e32 v61, 0xffff0000, v91
	v_lshlrev_b32_e32 v62, 16, v92
	v_and_b32_e32 v63, 0xffff0000, v92
	v_lshlrev_b32_e32 v64, 16, v93
	v_and_b32_e32 v65, 0xffff0000, v93
	v_pk_add_f32 v[56:57], v[56:57], v[60:61]
	v_pk_add_f32 v[54:55], v[54:55], v[58:59]
	v_pk_add_f32 v[60:61], v[50:51], v[62:63]
	v_cvt_pk_bf16_f32 v50, v54, v55
	v_cvt_pk_bf16_f32 v51, v56, v57
	v_pk_add_f32 v[58:59], v[52:53], v[64:65]
	v_cvt_pk_bf16_f32 v52, v60, v61
	s_nop 0
	v_cvt_pk_bf16_f32 v53, v58, v59
	v_mov_b32_dpp v252, v244 row_ror:8 row_mask:0xf bank_mask:0xf
	v_mov_b32_dpp v226, v50 row_ror:8 row_mask:0xf bank_mask:0xf
	v_cndmask_b32_e64 v50, v50, v252, s[98:99]
	v_cndmask_b32_e64 v244, v226, v244, s[98:99]
	v_mov_b32_dpp v252, v245 row_ror:8 row_mask:0xf bank_mask:0xf
	v_mov_b32_dpp v226, v51 row_ror:8 row_mask:0xf bank_mask:0xf
	v_cndmask_b32_e64 v51, v51, v252, s[98:99]
	v_cndmask_b32_e64 v245, v226, v245, s[98:99]
	v_mov_b32_dpp v252, v246 row_ror:8 row_mask:0xf bank_mask:0xf
	v_mov_b32_dpp v226, v52 row_ror:8 row_mask:0xf bank_mask:0xf
	v_cndmask_b32_e64 v52, v52, v252, s[98:99]
	v_cndmask_b32_e64 v246, v226, v246, s[98:99]
	v_mov_b32_dpp v252, v247 row_ror:8 row_mask:0xf bank_mask:0xf
	v_mov_b32_dpp v226, v53 row_ror:8 row_mask:0xf bank_mask:0xf
	v_cndmask_b32_e64 v53, v53, v252, s[98:99]
	v_cndmask_b32_e64 v247, v226, v247, s[98:99]
	v_lshl_add_u64 v[240:241], v[112:113], 0, v[250:251]
	v_lshl_add_u64 v[242:243], v[240:241], 0, s[100:101]
	flat_store_dwordx4 v[240:241], v[244:247]
	flat_store_dwordx4 v[242:243], v[50:53]
	s_nop 1
	v_mul_f32_e32 v50, v55, v55
	v_mul_f32_e32 v51, v57, v57
	v_fmac_f32_e32 v50, v54, v54
	v_fmac_f32_e32 v51, v56, v56
	v_add_f32_e32 v50, v50, v51
	v_mul_f32_e32 v51, v61, v61
	v_fmac_f32_e32 v51, v60, v60
	v_add_f32_e32 v50, v51, v50
	v_mul_f32_e32 v51, v59, v59
	v_fmac_f32_e32 v51, v58, v58
	v_add_f32_e32 v50, v51, v50
	v_add_f32_e32 v50, v108, v50
	ds_bpermute_b32 v51, v126, v50
	s_waitcnt lgkmcnt(0)
	v_add_f32_e32 v50, v50, v51
	ds_bpermute_b32 v51, v127, v50
	s_and_saveexec_b64 s[12:13], s[40:41]
	s_cbranch_execz .LBB0_639
	v_lshl_add_u64 v[52:53], v[106:107], 2, s[18:19]
	s_waitcnt lgkmcnt(0)
	v_add_f32_e32 v50, v50, v51
	flat_atomic_add_f32 v[52:53], v50
.LBB0_639:
	s_or_b64 exec, exec, s[12:13]
	v_lshlrev_b32_e32 v50, 16, v86
	s_waitcnt lgkmcnt(0)
	v_and_b32_e32 v51, 0xffff0000, v86
	v_lshlrev_b32_e32 v52, 16, v87
	v_and_b32_e32 v53, 0xffff0000, v87
	v_lshlrev_b32_e32 v54, 16, v88
	v_and_b32_e32 v55, 0xffff0000, v88
	v_pk_add_f32 v[46:47], v[46:47], v[50:51]
	v_pk_add_f32 v[48:49], v[48:49], v[52:53]
	v_pk_add_f32 v[52:53], v[42:43], v[54:55]
	v_cvt_pk_bf16_f32 v42, v46, v47
	v_mul_f32_e32 v47, v47, v47
	v_fmac_f32_e32 v47, v46, v46
	v_mul_f32_e32 v46, v49, v49
	v_fmac_f32_e32 v46, v48, v48
	v_lshlrev_b32_e32 v56, 16, v89
	v_and_b32_e32 v57, 0xffff0000, v89
	v_add_f32_e32 v46, v47, v46
	v_mul_f32_e32 v47, v53, v53
	v_pk_add_f32 v[50:51], v[44:45], v[56:57]
	v_fmac_f32_e32 v47, v52, v52
	v_add_f32_e32 v46, v47, v46
	v_mul_f32_e32 v47, v51, v51
	v_fmac_f32_e32 v47, v50, v50
	v_cvt_pk_bf16_f32 v43, v48, v49
	v_add_f32_e32 v54, v47, v46
	v_lshlrev_b32_e32 v46, 16, v82
	v_and_b32_e32 v47, 0xffff0000, v82
	v_lshlrev_b32_e32 v48, 16, v83
	v_and_b32_e32 v49, 0xffff0000, v83
	v_cvt_pk_bf16_f32 v44, v52, v53
	v_cvt_pk_bf16_f32 v45, v50, v51
	v_lshlrev_b32_e32 v50, 16, v84
	v_and_b32_e32 v51, 0xffff0000, v84
	v_pk_add_f32 v[40:41], v[40:41], v[48:49]
	v_pk_add_f32 v[38:39], v[38:39], v[46:47]
	v_pk_add_f32 v[48:49], v[34:35], v[50:51]
	v_mul_f32_e32 v34, v39, v39
	v_mul_f32_e32 v35, v41, v41
	v_fmac_f32_e32 v34, v38, v38
	v_fmac_f32_e32 v35, v40, v40
	v_lshlrev_b32_e32 v52, 16, v85
	v_and_b32_e32 v53, 0xffff0000, v85
	v_add_f32_e32 v34, v34, v35
	v_mul_f32_e32 v35, v49, v49
	v_pk_add_f32 v[46:47], v[36:37], v[52:53]
	v_fmac_f32_e32 v35, v48, v48
	v_add_f32_e32 v34, v35, v34
	v_mul_f32_e32 v35, v47, v47
	v_fmac_f32_e32 v35, v46, v46
	v_add_f32_e32 v34, v35, v34
	v_add_f32_e32 v37, v54, v34
	ds_bpermute_b32 v52, v126, v37
	v_lshl_add_u64 v[34:35], s[46:47], 0, v[104:105]
	v_lshl_add_u64 v[50:51], v[164:165], 1, v[34:35]
	v_mov_b32_e32 v244, v42
	v_mov_b32_e32 v245, v43
	v_mov_b32_e32 v246, v44
	v_mov_b32_e32 v247, v45
	v_cvt_pk_bf16_f32 v36, v38, v39
	s_waitcnt lgkmcnt(0)
	v_add_f32_e32 v34, v37, v52
	ds_bpermute_b32 v35, v127, v34
	v_cvt_pk_bf16_f32 v37, v40, v41
	v_cvt_pk_bf16_f32 v38, v48, v49
	v_cvt_pk_bf16_f32 v39, v46, v47
	v_mov_b32_dpp v252, v244 row_ror:8 row_mask:0xf bank_mask:0xf
	v_mov_b32_dpp v226, v36 row_ror:8 row_mask:0xf bank_mask:0xf
	v_cndmask_b32_e64 v36, v36, v252, s[98:99]
	v_cndmask_b32_e64 v244, v226, v244, s[98:99]
	v_mov_b32_dpp v252, v245 row_ror:8 row_mask:0xf bank_mask:0xf
	v_mov_b32_dpp v226, v37 row_ror:8 row_mask:0xf bank_mask:0xf
	v_cndmask_b32_e64 v37, v37, v252, s[98:99]
	v_cndmask_b32_e64 v245, v226, v245, s[98:99]
	v_mov_b32_dpp v252, v246 row_ror:8 row_mask:0xf bank_mask:0xf
	v_mov_b32_dpp v226, v38 row_ror:8 row_mask:0xf bank_mask:0xf
	v_cndmask_b32_e64 v38, v38, v252, s[98:99]
	v_cndmask_b32_e64 v246, v226, v246, s[98:99]
	v_mov_b32_dpp v252, v247 row_ror:8 row_mask:0xf bank_mask:0xf
	v_mov_b32_dpp v226, v39 row_ror:8 row_mask:0xf bank_mask:0xf
	v_cndmask_b32_e64 v39, v39, v252, s[98:99]
	v_cndmask_b32_e64 v247, v226, v247, s[98:99]
	v_lshl_add_u64 v[240:241], v[50:51], 0, v[250:251]
	v_lshl_add_u64 v[242:243], v[240:241], 0, s[100:101]
	flat_store_dwordx4 v[240:241], v[244:247]
	flat_store_dwordx4 v[242:243], v[36:39]
	s_and_saveexec_b64 s[12:13], s[40:41]
	s_cbranch_execz .LBB0_641
	v_lshl_add_u64 v[36:37], v[102:103], 2, s[18:19]
	s_waitcnt lgkmcnt(0)
	v_add_f32_e32 v34, v34, v35
	flat_atomic_add_f32 v[36:37], v34
.LBB0_641:
	s_or_b64 exec, exec, s[12:13]
	v_lshlrev_b32_e32 v34, 16, v78
	s_waitcnt lgkmcnt(0)
	v_and_b32_e32 v35, 0xffff0000, v78
	v_lshlrev_b32_e32 v36, 16, v79
	v_and_b32_e32 v37, 0xffff0000, v79
	v_lshlrev_b32_e32 v38, 16, v80
	v_and_b32_e32 v39, 0xffff0000, v80
	v_pk_add_f32 v[30:31], v[30:31], v[34:35]
	v_pk_add_f32 v[32:33], v[32:33], v[36:37]
	v_pk_add_f32 v[36:37], v[26:27], v[38:39]
	v_cvt_pk_bf16_f32 v26, v30, v31
	v_mul_f32_e32 v31, v31, v31
	v_fmac_f32_e32 v31, v30, v30
	v_mul_f32_e32 v30, v33, v33
	v_fmac_f32_e32 v30, v32, v32
	v_lshlrev_b32_e32 v40, 16, v81
	v_and_b32_e32 v41, 0xffff0000, v81
	v_add_f32_e32 v30, v31, v30
	v_mul_f32_e32 v31, v37, v37
	v_pk_add_f32 v[34:35], v[28:29], v[40:41]
	v_fmac_f32_e32 v31, v36, v36
	v_add_f32_e32 v30, v31, v30
	v_mul_f32_e32 v31, v35, v35
	v_fmac_f32_e32 v31, v34, v34
	v_cvt_pk_bf16_f32 v27, v32, v33
	v_add_f32_e32 v38, v31, v30
	v_lshlrev_b32_e32 v30, 16, v74
	v_and_b32_e32 v31, 0xffff0000, v74
	v_lshlrev_b32_e32 v32, 16, v75
	v_and_b32_e32 v33, 0xffff0000, v75
	v_cvt_pk_bf16_f32 v28, v36, v37
	v_cvt_pk_bf16_f32 v29, v34, v35
	v_lshlrev_b32_e32 v34, 16, v76
	v_and_b32_e32 v35, 0xffff0000, v76
	v_pk_add_f32 v[24:25], v[24:25], v[32:33]
	v_pk_add_f32 v[22:23], v[22:23], v[30:31]
	v_pk_add_f32 v[32:33], v[18:19], v[34:35]
	v_mul_f32_e32 v18, v23, v23
	v_mul_f32_e32 v19, v25, v25
	v_fmac_f32_e32 v18, v22, v22
	v_fmac_f32_e32 v19, v24, v24
	v_lshlrev_b32_e32 v36, 16, v77
	v_and_b32_e32 v37, 0xffff0000, v77
	v_add_f32_e32 v18, v18, v19
	v_mul_f32_e32 v19, v33, v33
	v_pk_add_f32 v[30:31], v[20:21], v[36:37]
	v_fmac_f32_e32 v19, v32, v32
	v_add_f32_e32 v18, v19, v18
	v_mul_f32_e32 v19, v31, v31
	v_fmac_f32_e32 v19, v30, v30
	v_add_f32_e32 v18, v19, v18
	v_add_f32_e32 v21, v38, v18
	ds_bpermute_b32 v36, v126, v21
	v_lshl_add_u64 v[18:19], s[46:47], 0, v[100:101]
	v_lshl_add_u64 v[34:35], v[164:165], 1, v[18:19]
	v_mov_b32_e32 v244, v26
	v_mov_b32_e32 v245, v27
	v_mov_b32_e32 v246, v28
	v_mov_b32_e32 v247, v29
	v_cvt_pk_bf16_f32 v20, v22, v23
	s_waitcnt lgkmcnt(0)
	v_add_f32_e32 v18, v21, v36
	ds_bpermute_b32 v19, v127, v18
	v_cvt_pk_bf16_f32 v21, v24, v25
	v_cvt_pk_bf16_f32 v22, v32, v33
	v_cvt_pk_bf16_f32 v23, v30, v31
	v_mov_b32_dpp v252, v244 row_ror:8 row_mask:0xf bank_mask:0xf
	v_mov_b32_dpp v226, v20 row_ror:8 row_mask:0xf bank_mask:0xf
	v_cndmask_b32_e64 v20, v20, v252, s[98:99]
	v_cndmask_b32_e64 v244, v226, v244, s[98:99]
	v_mov_b32_dpp v252, v245 row_ror:8 row_mask:0xf bank_mask:0xf
	v_mov_b32_dpp v226, v21 row_ror:8 row_mask:0xf bank_mask:0xf
	v_cndmask_b32_e64 v21, v21, v252, s[98:99]
	v_cndmask_b32_e64 v245, v226, v245, s[98:99]
	v_mov_b32_dpp v252, v246 row_ror:8 row_mask:0xf bank_mask:0xf
	v_mov_b32_dpp v226, v22 row_ror:8 row_mask:0xf bank_mask:0xf
	v_cndmask_b32_e64 v22, v22, v252, s[98:99]
	v_cndmask_b32_e64 v246, v226, v246, s[98:99]
	v_mov_b32_dpp v252, v247 row_ror:8 row_mask:0xf bank_mask:0xf
	v_mov_b32_dpp v226, v23 row_ror:8 row_mask:0xf bank_mask:0xf
	v_cndmask_b32_e64 v23, v23, v252, s[98:99]
	v_cndmask_b32_e64 v247, v226, v247, s[98:99]
	v_lshl_add_u64 v[240:241], v[34:35], 0, v[250:251]
	v_lshl_add_u64 v[242:243], v[240:241], 0, s[100:101]
	flat_store_dwordx4 v[240:241], v[244:247]
	flat_store_dwordx4 v[242:243], v[20:23]
	s_and_saveexec_b64 s[12:13], s[40:41]
	s_cbranch_execz .LBB0_643
	v_lshl_add_u64 v[20:21], v[98:99], 2, s[18:19]
	s_waitcnt lgkmcnt(0)
	v_add_f32_e32 v18, v18, v19
	flat_atomic_add_f32 v[20:21], v18
.LBB0_643:
	s_or_b64 exec, exec, s[12:13]
	v_lshlrev_b32_e32 v18, 16, v70
	s_waitcnt lgkmcnt(0)
	v_and_b32_e32 v19, 0xffff0000, v70
	v_lshlrev_b32_e32 v20, 16, v71
	v_and_b32_e32 v21, 0xffff0000, v71
	v_lshlrev_b32_e32 v22, 16, v72
	v_and_b32_e32 v23, 0xffff0000, v72
	v_pk_add_f32 v[14:15], v[14:15], v[18:19]
	v_pk_add_f32 v[16:17], v[16:17], v[20:21]
	v_pk_add_f32 v[20:21], v[10:11], v[22:23]
	v_cvt_pk_bf16_f32 v10, v14, v15
	v_mul_f32_e32 v15, v15, v15
	v_fmac_f32_e32 v15, v14, v14
	v_mul_f32_e32 v14, v17, v17
	v_fmac_f32_e32 v14, v16, v16
	v_lshlrev_b32_e32 v24, 16, v73
	v_and_b32_e32 v25, 0xffff0000, v73
	v_add_f32_e32 v14, v15, v14
	v_mul_f32_e32 v15, v21, v21
	v_pk_add_f32 v[18:19], v[12:13], v[24:25]
	v_fmac_f32_e32 v15, v20, v20
	v_add_f32_e32 v14, v15, v14
	v_mul_f32_e32 v15, v19, v19
	v_fmac_f32_e32 v15, v18, v18
	v_cvt_pk_bf16_f32 v11, v16, v17
	v_add_f32_e32 v22, v15, v14
	v_lshlrev_b32_e32 v14, 16, v66
	v_and_b32_e32 v15, 0xffff0000, v66
	v_lshlrev_b32_e32 v16, 16, v67
	v_and_b32_e32 v17, 0xffff0000, v67
	v_cvt_pk_bf16_f32 v12, v20, v21
	v_cvt_pk_bf16_f32 v13, v18, v19
	v_lshlrev_b32_e32 v18, 16, v68
	v_and_b32_e32 v19, 0xffff0000, v68
	v_pk_add_f32 v[8:9], v[8:9], v[16:17]
	v_pk_add_f32 v[6:7], v[6:7], v[14:15]
	v_pk_add_f32 v[16:17], v[2:3], v[18:19]
	v_mul_f32_e32 v2, v7, v7
	v_mul_f32_e32 v3, v9, v9
	v_fmac_f32_e32 v2, v6, v6
	v_fmac_f32_e32 v3, v8, v8
	v_lshlrev_b32_e32 v20, 16, v69
	v_and_b32_e32 v21, 0xffff0000, v69
	v_add_f32_e32 v2, v2, v3
	v_mul_f32_e32 v3, v17, v17
	v_pk_add_f32 v[14:15], v[4:5], v[20:21]
	v_fmac_f32_e32 v3, v16, v16
	v_add_f32_e32 v2, v3, v2
	v_mul_f32_e32 v3, v15, v15
	v_fmac_f32_e32 v3, v14, v14
	v_add_f32_e32 v2, v3, v2
	v_add_f32_e32 v5, v22, v2
	ds_bpermute_b32 v20, v126, v5
	v_lshl_add_u64 v[2:3], s[46:47], 0, v[96:97]
	v_lshl_add_u64 v[18:19], v[164:165], 1, v[2:3]
	v_mov_b32_e32 v244, v10
	v_mov_b32_e32 v245, v11
	v_mov_b32_e32 v246, v12
	v_mov_b32_e32 v247, v13
	v_cvt_pk_bf16_f32 v4, v6, v7
	s_waitcnt lgkmcnt(0)
	v_add_f32_e32 v2, v5, v20
	ds_bpermute_b32 v3, v127, v2
	v_cvt_pk_bf16_f32 v5, v8, v9
	v_cvt_pk_bf16_f32 v6, v16, v17
	v_cvt_pk_bf16_f32 v7, v14, v15
	v_mov_b32_dpp v252, v244 row_ror:8 row_mask:0xf bank_mask:0xf
	v_mov_b32_dpp v226, v4 row_ror:8 row_mask:0xf bank_mask:0xf
	v_cndmask_b32_e64 v4, v4, v252, s[98:99]
	v_cndmask_b32_e64 v244, v226, v244, s[98:99]
	v_mov_b32_dpp v252, v245 row_ror:8 row_mask:0xf bank_mask:0xf
	v_mov_b32_dpp v226, v5 row_ror:8 row_mask:0xf bank_mask:0xf
	v_cndmask_b32_e64 v5, v5, v252, s[98:99]
	v_cndmask_b32_e64 v245, v226, v245, s[98:99]
	v_mov_b32_dpp v252, v246 row_ror:8 row_mask:0xf bank_mask:0xf
	v_mov_b32_dpp v226, v6 row_ror:8 row_mask:0xf bank_mask:0xf
	v_cndmask_b32_e64 v6, v6, v252, s[98:99]
	v_cndmask_b32_e64 v246, v226, v246, s[98:99]
	v_mov_b32_dpp v252, v247 row_ror:8 row_mask:0xf bank_mask:0xf
	v_mov_b32_dpp v226, v7 row_ror:8 row_mask:0xf bank_mask:0xf
	v_cndmask_b32_e64 v7, v7, v252, s[98:99]
	v_cndmask_b32_e64 v247, v226, v247, s[98:99]
	v_lshl_add_u64 v[240:241], v[18:19], 0, v[250:251]
	v_lshl_add_u64 v[242:243], v[240:241], 0, s[100:101]
	flat_store_dwordx4 v[240:241], v[244:247]
	flat_store_dwordx4 v[242:243], v[4:7]
	s_and_saveexec_b64 s[12:13], s[40:41]
	s_cbranch_execz .LBB0_645
	v_lshl_add_u64 v[4:5], v[94:95], 2, s[18:19]
	s_waitcnt lgkmcnt(0)
	v_add_f32_e32 v2, v2, v3
	flat_atomic_add_f32 v[4:5], v2
